# transpose items: 8 LDS column reads in flight instead of a serial read-wait-cvt chain (6 sites), on cp3
# speedup vs baseline: 1.0089x; 1.0089x over previous
; #define LAS __attribute__((address_space(3)))
; template <bool MAP> __device__ __forceinline__ void p0_transpose_item(const float* W, int K, int NS, bf16* WT, LAS float* scr, int item, int nkb, int lane) {
;     const int pb = item / nkb, kb = item % nkb, k0 = 64 * kb, p0 = 32 * pb;
;     const int sc = MAP ? pg8::proj_src_col(p0 + (lane & 31)) : p0 + (lane & 31);
; #pragma unroll 8
;     for (int i = 0; i < 32; ++i) { const int kk = 2 * i + (lane >> 5); scr[kk * 33 + (lane & 31)] = W[(size_t)(k0 + kk) * NS + sc]; }
.LBB0_57:
	s_lshl_b32 s20, s6, 1
	s_lshl_b32 s21, s7, 1
	v_or_b32_e32 v5, s20, v1
	v_or_b32_e32 v7, s21, v4
	s_add_i32 s22, s20, 4
	s_add_i32 s23, s21, 4
	s_add_i32 s26, s20, 8
	s_add_i32 s27, s21, 8
	s_add_i32 s28, s20, 12
	s_add_i32 s29, s21, 12
	s_add_i32 s30, s20, 16
	s_add_i32 s31, s21, 16
	s_add_i32 s33, s20, 20
	s_add_i32 s34, s21, 20
	s_add_i32 s35, s20, 24
	s_add_i32 s36, s21, 24
	s_add_i32 s20, s20, 28
	s_add_i32 s21, s21, 28
	v_add_u32_e32 v10, s14, v5
	v_add_u32_e32 v13, s4, v7
	v_or_b32_e32 v17, s22, v1
	v_or_b32_e32 v48, s23, v4
	v_or_b32_e32 v49, s26, v1
	v_or_b32_e32 v50, s27, v4
	v_or_b32_e32 v51, s28, v1
	v_or_b32_e32 v52, s29, v4
	v_or_b32_e32 v53, s30, v1
	v_or_b32_e32 v54, s31, v4
	v_or_b32_e32 v55, s33, v1
	v_or_b32_e32 v56, s34, v4
	v_or_b32_e32 v57, s35, v1
	v_or_b32_e32 v58, s36, v4
	v_or_b32_e32 v59, s20, v1
	v_or_b32_e32 v60, s21, v4
	v_mul_lo_u32 v14, v13, s16
	v_mul_lo_u32 v18, v10, s16
	v_add_u32_e32 v10, s14, v17
	v_add_u32_e32 v13, s4, v48
	v_add_u32_e32 v21, s14, v49
	v_add_u32_e32 v23, s4, v50
	v_add_u32_e32 v25, s14, v51
	v_add_u32_e32 v27, s4, v52
	v_add_u32_e32 v29, s14, v53
	v_add_u32_e32 v31, s4, v54
	v_add_u32_e32 v33, s14, v55
	v_add_u32_e32 v35, s4, v56
	v_add_u32_e32 v37, s14, v57
	v_add_u32_e32 v39, s4, v58
	v_add_u32_e32 v41, s14, v59
	v_add_u32_e32 v43, s4, v60
	v_ashrrev_i32_e32 v15, 31, v14
	v_mul_lo_u32 v20, v13, s16
	v_mul_lo_u32 v22, v10, s16
	v_mul_lo_u32 v24, v23, s16
	v_mul_lo_u32 v26, v21, s16
	v_mul_lo_u32 v28, v27, s16
	v_mul_lo_u32 v30, v25, s16
	v_mul_lo_u32 v32, v31, s16
	v_mul_lo_u32 v34, v29, s16
	v_mul_lo_u32 v36, v35, s16
	v_mul_lo_u32 v38, v33, s16
	v_mul_lo_u32 v40, v39, s16
	v_mul_lo_u32 v42, v37, s16
	v_mul_lo_u32 v44, v43, s16
	v_mul_lo_u32 v46, v41, s16
	v_ashrrev_i32_e32 v19, 31, v18
	v_lshl_add_u64 v[14:15], v[14:15], 2, v[8:9]
	v_ashrrev_i32_e32 v23, 31, v22
	v_ashrrev_i32_e32 v21, 31, v20
	v_ashrrev_i32_e32 v27, 31, v26
	v_ashrrev_i32_e32 v25, 31, v24
	v_ashrrev_i32_e32 v31, 31, v30
	v_ashrrev_i32_e32 v29, 31, v28
	v_ashrrev_i32_e32 v35, 31, v34
	v_ashrrev_i32_e32 v33, 31, v32
	v_ashrrev_i32_e32 v39, 31, v38
	v_ashrrev_i32_e32 v37, 31, v36
	v_ashrrev_i32_e32 v43, 31, v42
	v_ashrrev_i32_e32 v41, 31, v40
	v_ashrrev_i32_e32 v47, 31, v46
	v_ashrrev_i32_e32 v45, 31, v44
	v_lshl_add_u64 v[18:19], v[18:19], 2, v[8:9]
	v_lshl_add_u64 v[20:21], v[20:21], 2, v[8:9]
	v_lshl_add_u64 v[22:23], v[22:23], 2, v[8:9]
	v_lshl_add_u64 v[24:25], v[24:25], 2, v[8:9]
	v_lshl_add_u64 v[26:27], v[26:27], 2, v[8:9]
	v_lshl_add_u64 v[28:29], v[28:29], 2, v[8:9]
	v_lshl_add_u64 v[30:31], v[30:31], 2, v[8:9]
	v_lshl_add_u64 v[32:33], v[32:33], 2, v[8:9]
	v_lshl_add_u64 v[34:35], v[34:35], 2, v[8:9]
	v_lshl_add_u64 v[36:37], v[36:37], 2, v[8:9]
	v_lshl_add_u64 v[38:39], v[38:39], 2, v[8:9]
	v_lshl_add_u64 v[40:41], v[40:41], 2, v[8:9]
	v_lshl_add_u64 v[42:43], v[42:43], 2, v[8:9]
	v_lshl_add_u64 v[44:45], v[44:45], 2, v[8:9]
	v_lshl_add_u64 v[46:47], v[46:47], 2, v[8:9]
	global_load_dword v10, v[14:15], off
	global_load_dword v13, v[18:19], off
	global_load_dword v61, v[20:21], off
	global_load_dword v62, v[22:23], off
	global_load_dword v63, v[24:25], off
	global_load_dword v64, v[26:27], off
	global_load_dword v65, v[28:29], off
	global_load_dword v66, v[30:31], off
	global_load_dword v67, v[32:33], off
	global_load_dword v68, v[34:35], off
	global_load_dword v69, v[36:37], off
	global_load_dword v70, v[38:39], off
	global_load_dword v71, v[40:41], off
	global_load_dword v72, v[42:43], off
	global_load_dword v73, v[44:45], off
	global_load_dword v74, v[46:47], off
	s_add_i32 s7, s7, 16
	s_add_i32 s6, s6, 16
	s_add_i32 s15, s15, -16
	v_mad_u64_u32 v[14:15], s[20:21], v7, s17, v[6:7]
	s_cmp_lg_u32 s15, 0
	v_mad_u64_u32 v[18:19], s[20:21], v5, s17, v[6:7]
	v_mad_u64_u32 v[20:21], s[20:21], v48, s17, v[6:7]
	v_mad_u64_u32 v[22:23], s[20:21], v17, s17, v[6:7]
	v_mad_u64_u32 v[24:25], s[20:21], v50, s17, v[6:7]
	v_mad_u64_u32 v[26:27], s[20:21], v49, s17, v[6:7]
	v_mad_u64_u32 v[28:29], s[20:21], v52, s17, v[6:7]
	v_mad_u64_u32 v[30:31], s[20:21], v51, s17, v[6:7]
	v_mad_u64_u32 v[32:33], s[20:21], v54, s17, v[6:7]
	v_mad_u64_u32 v[34:35], s[20:21], v53, s17, v[6:7]
	v_mad_u64_u32 v[36:37], s[20:21], v56, s17, v[6:7]
	v_mad_u64_u32 v[38:39], s[20:21], v55, s17, v[6:7]
	v_mad_u64_u32 v[40:41], s[20:21], v58, s17, v[6:7]
	v_mad_u64_u32 v[42:43], s[20:21], v57, s17, v[6:7]
	v_mad_u64_u32 v[44:45], s[20:21], v60, s17, v[6:7]
	v_mad_u64_u32 v[46:47], s[20:21], v59, s17, v[6:7]
	s_lshl_b32 s20, s6, 1
	s_lshl_b32 s21, s7, 1
	v_or_b32_e32 v105, s20, v1
	v_or_b32_e32 v107, s21, v4
	s_add_i32 s22, s20, 4
	s_add_i32 s23, s21, 4
	s_add_i32 s26, s20, 8
	s_add_i32 s27, s21, 8
	s_add_i32 s28, s20, 12
	s_add_i32 s29, s21, 12
	s_add_i32 s30, s20, 16
	s_add_i32 s31, s21, 16
	s_add_i32 s33, s20, 20
	s_add_i32 s34, s21, 20
	s_add_i32 s35, s20, 24
	s_add_i32 s36, s21, 24
	s_add_i32 s20, s20, 28
	s_add_i32 s21, s21, 28
	v_add_u32_e32 v110, s14, v105
	v_add_u32_e32 v113, s4, v107
	v_or_b32_e32 v117, s22, v1
	v_or_b32_e32 v148, s23, v4
	v_or_b32_e32 v149, s26, v1
	v_or_b32_e32 v150, s27, v4
	v_or_b32_e32 v151, s28, v1
	v_or_b32_e32 v152, s29, v4
	v_or_b32_e32 v153, s30, v1
	v_or_b32_e32 v154, s31, v4
	v_or_b32_e32 v155, s33, v1
	v_or_b32_e32 v156, s34, v4
	v_or_b32_e32 v157, s35, v1
	v_or_b32_e32 v158, s36, v4
	v_or_b32_e32 v159, s20, v1
	v_or_b32_e32 v160, s21, v4
	v_mul_lo_u32 v114, v113, s16
	v_mul_lo_u32 v118, v110, s16
	v_add_u32_e32 v110, s14, v117
	v_add_u32_e32 v113, s4, v148
	v_add_u32_e32 v121, s14, v149
	v_add_u32_e32 v123, s4, v150
	v_add_u32_e32 v125, s14, v151
	v_add_u32_e32 v127, s4, v152
; template <bool MAP> __device__ __forceinline__ void p0_transpose_item(const float* W, int K, int NS, bf16* WT, LAS float* scr, int item, int nkb, int lane) {
;     ...
;     for (int i = 0; i < 32; ++i) { const int kk = 2 * i + (lane >> 5); scr[kk * 33 + (lane & 31)] = W[(size_t)(k0 + kk) * NS + sc]; }
	v_add_u32_e32 v129, s14, v153
	v_add_u32_e32 v131, s4, v154
	v_add_u32_e32 v133, s14, v155
	v_add_u32_e32 v135, s4, v156
	v_add_u32_e32 v137, s14, v157
	v_add_u32_e32 v139, s4, v158
	v_add_u32_e32 v141, s14, v159
	v_add_u32_e32 v143, s4, v160
	v_ashrrev_i32_e32 v115, 31, v114
	v_mul_lo_u32 v120, v113, s16
	v_mul_lo_u32 v122, v110, s16
	v_mul_lo_u32 v124, v123, s16
	v_mul_lo_u32 v126, v121, s16
	v_mul_lo_u32 v128, v127, s16
	v_mul_lo_u32 v130, v125, s16
	v_mul_lo_u32 v132, v131, s16
	v_mul_lo_u32 v134, v129, s16
	v_mul_lo_u32 v136, v135, s16
	v_mul_lo_u32 v138, v133, s16
	v_mul_lo_u32 v140, v139, s16
	v_mul_lo_u32 v142, v137, s16
	v_mul_lo_u32 v144, v143, s16
	v_mul_lo_u32 v146, v141, s16
	v_ashrrev_i32_e32 v119, 31, v118
	v_lshl_add_u64 v[114:115], v[114:115], 2, v[8:9]
	v_ashrrev_i32_e32 v123, 31, v122
	v_ashrrev_i32_e32 v121, 31, v120
	v_ashrrev_i32_e32 v127, 31, v126
	v_ashrrev_i32_e32 v125, 31, v124
	v_ashrrev_i32_e32 v131, 31, v130
	v_ashrrev_i32_e32 v129, 31, v128
	v_ashrrev_i32_e32 v135, 31, v134
	v_ashrrev_i32_e32 v133, 31, v132
	v_ashrrev_i32_e32 v139, 31, v138
	v_ashrrev_i32_e32 v137, 31, v136
	v_ashrrev_i32_e32 v143, 31, v142
	v_ashrrev_i32_e32 v141, 31, v140
	v_ashrrev_i32_e32 v147, 31, v146
	v_ashrrev_i32_e32 v145, 31, v144
	v_lshl_add_u64 v[118:119], v[118:119], 2, v[8:9]
	v_lshl_add_u64 v[120:121], v[120:121], 2, v[8:9]
	v_lshl_add_u64 v[122:123], v[122:123], 2, v[8:9]
	v_lshl_add_u64 v[124:125], v[124:125], 2, v[8:9]
	v_lshl_add_u64 v[126:127], v[126:127], 2, v[8:9]
	v_lshl_add_u64 v[128:129], v[128:129], 2, v[8:9]
	v_lshl_add_u64 v[130:131], v[130:131], 2, v[8:9]
	v_lshl_add_u64 v[132:133], v[132:133], 2, v[8:9]
	v_lshl_add_u64 v[134:135], v[134:135], 2, v[8:9]
	v_lshl_add_u64 v[136:137], v[136:137], 2, v[8:9]
	v_lshl_add_u64 v[138:139], v[138:139], 2, v[8:9]
	v_lshl_add_u64 v[140:141], v[140:141], 2, v[8:9]
	v_lshl_add_u64 v[142:143], v[142:143], 2, v[8:9]
	v_lshl_add_u64 v[144:145], v[144:145], 2, v[8:9]
	v_lshl_add_u64 v[146:147], v[146:147], 2, v[8:9]
	global_load_dword v110, v[114:115], off
	global_load_dword v113, v[118:119], off
	global_load_dword v161, v[120:121], off
	global_load_dword v162, v[122:123], off
	global_load_dword v163, v[124:125], off
	global_load_dword v164, v[126:127], off
	global_load_dword v165, v[128:129], off
	global_load_dword v166, v[130:131], off
	global_load_dword v167, v[132:133], off
	global_load_dword v168, v[134:135], off
	global_load_dword v169, v[136:137], off
	global_load_dword v170, v[138:139], off
	global_load_dword v171, v[140:141], off
	global_load_dword v172, v[142:143], off
	global_load_dword v173, v[144:145], off
	global_load_dword v174, v[146:147], off
	s_waitcnt vmcnt(31)
	ds_write_b32 v14, v10
	s_waitcnt vmcnt(30)
	ds_write_b32 v18, v13
	s_waitcnt vmcnt(29)
	ds_write_b32 v20, v61
	s_waitcnt vmcnt(28)
	ds_write_b32 v22, v62
	s_waitcnt vmcnt(27)
	ds_write_b32 v24, v63
	s_waitcnt vmcnt(26)
	ds_write_b32 v26, v64
	s_waitcnt vmcnt(25)
	ds_write_b32 v28, v65
	s_waitcnt vmcnt(24)
	ds_write_b32 v30, v66
	s_waitcnt vmcnt(23)
	ds_write_b32 v32, v67
	s_waitcnt vmcnt(22)
	ds_write_b32 v34, v68
	s_waitcnt vmcnt(21)
	ds_write_b32 v36, v69
	s_waitcnt vmcnt(20)
	ds_write_b32 v38, v70
	s_waitcnt vmcnt(19)
	ds_write_b32 v40, v71
	s_waitcnt vmcnt(18)
	ds_write_b32 v42, v72
	s_waitcnt vmcnt(17)
	ds_write_b32 v44, v73
	s_waitcnt vmcnt(16)
	ds_write_b32 v46, v74
	s_add_i32 s7, s7, 16
	s_add_i32 s6, s6, 16
	s_add_i32 s15, s15, -16
	v_mad_u64_u32 v[14:15], s[20:21], v107, s17, v[6:7]
	s_cmp_lg_u32 s15, 0
	v_mad_u64_u32 v[18:19], s[20:21], v105, s17, v[6:7]
	v_mad_u64_u32 v[20:21], s[20:21], v148, s17, v[6:7]
	v_mad_u64_u32 v[22:23], s[20:21], v117, s17, v[6:7]
	v_mad_u64_u32 v[24:25], s[20:21], v150, s17, v[6:7]
	v_mad_u64_u32 v[26:27], s[20:21], v149, s17, v[6:7]
	v_mad_u64_u32 v[28:29], s[20:21], v152, s17, v[6:7]
	v_mad_u64_u32 v[30:31], s[20:21], v151, s17, v[6:7]
	v_mad_u64_u32 v[32:33], s[20:21], v154, s17, v[6:7]
	v_mad_u64_u32 v[34:35], s[20:21], v153, s17, v[6:7]
	v_mad_u64_u32 v[36:37], s[20:21], v156, s17, v[6:7]
	v_mad_u64_u32 v[38:39], s[20:21], v155, s17, v[6:7]
	v_mad_u64_u32 v[40:41], s[20:21], v158, s17, v[6:7]
	v_mad_u64_u32 v[42:43], s[20:21], v157, s17, v[6:7]
	v_mad_u64_u32 v[44:45], s[20:21], v160, s17, v[6:7]
	v_mad_u64_u32 v[46:47], s[20:21], v159, s17, v[6:7]
	s_waitcnt vmcnt(15)
; #define GAS __attribute__((address_space(1)))
; #define LAS __attribute__((address_space(3)))
; #define LDS_WAIT() asm volatile("s_waitcnt lgkmcnt(0)" ::: "memory")
; __device__ __forceinline__ unsigned pk2(float lo, float hi) { return pg8::cvt_pk_bf16(lo, hi); }
; __host__ __device__ __forceinline__ int proj_src_col(int p) {
;     const int pn = p >> 8, r = p & 255, bj = r >> 7, wc = (r >> 5) & 3, jj = r & 31;
;     if (pn >= 8 && pn < 16) { const int fq = jj >> 3, n = (jj >> 2) & 1, i = jj & 3; const int sect = bj == 0 ? (n == 0 ? 2056 : 2568) : (n == 0 ? 3080 : 3592); return sect + 64 * (pn - 8) + 16 * wc + 4 * fq + i; }
;     if (pn >= 16) return (bj == 0 ? 4104 : 5128) + 128 * (pn - 16) + 32 * wc + jj;
;     const int nat = 64 * wc + 32 * bj + jj;
;     if (pn < 6) return 256 * pn + nat;
;     return 1544 + 256 * (pn - 6) + nat;
; }
; template <bool MAP> __device__ __forceinline__ void p0_transpose_item(const float* W, int K, int NS, bf16* WT, LAS float* scr, int item, int nkb, int lane) {
;     ...
;     for (int i = 0; i < 32; ++i) { const int kk = 2 * i + (lane >> 5); scr[kk * 33 + (lane & 31)] = W[(size_t)(k0 + kk) * NS + sc]; }
;     LDS_WAIT(); asm volatile("" ::: "memory");
;     const int c = lane & 7;
; #pragma unroll
;     for (int j = 0; j < 4; ++j) { const int n = (lane >> 3) + 8 * j; const LAS float* s = scr + (8 * c) * 33 + n;
;         v4u o; o.x = pk2(s[0 * 33], s[1 * 33]); o.y = pk2(s[2 * 33], s[3 * 33]); o.z = pk2(s[4 * 33], s[5 * 33]); o.w = pk2(s[6 * 33], s[7 * 33]);
;         *(GAS v4u*)(WT + (size_t)(p0 + n) * K + k0 + 8 * c) = o; }
;     LDS_WAIT(); asm volatile("" ::: "memory");
	ds_write_b32 v14, v110
	s_waitcnt vmcnt(14)
	ds_write_b32 v18, v113
	s_waitcnt vmcnt(13)
	ds_write_b32 v20, v161
	s_waitcnt vmcnt(12)
	ds_write_b32 v22, v162
	s_waitcnt vmcnt(11)
	ds_write_b32 v24, v163
	s_waitcnt vmcnt(10)
	ds_write_b32 v26, v164
	s_waitcnt vmcnt(9)
	ds_write_b32 v28, v165
	s_waitcnt vmcnt(8)
	ds_write_b32 v30, v166
	s_waitcnt vmcnt(7)
	ds_write_b32 v32, v167
	s_waitcnt vmcnt(6)
	ds_write_b32 v34, v168
	s_waitcnt vmcnt(5)
	ds_write_b32 v36, v169
	s_waitcnt vmcnt(4)
	ds_write_b32 v38, v170
	s_waitcnt vmcnt(3)
	ds_write_b32 v40, v171
	s_waitcnt vmcnt(2)
	ds_write_b32 v42, v172
	s_waitcnt vmcnt(1)
	ds_write_b32 v44, v173
	s_waitcnt vmcnt(0)
	ds_write_b32 v46, v174
	v_lshlrev_b32_e32 v5, 3, v16
	v_lshrrev_b32_e32 v7, 3, v16
	v_and_b32_e32 v10, 56, v5
	s_waitcnt lgkmcnt(0)
	v_mul_u32_u24_e32 v5, 0x84, v10
	v_lshlrev_b32_e32 v8, 2, v7
	v_add3_u32 v5, s5, v5, v8
	ds_read2_b32 v[62:63], v5 offset1:33
	ds_read2_b32 v[64:65], v5 offset0:66 offset1:99
	ds_read2_b32 v[66:67], v5 offset0:132 offset1:165
	ds_read2_b32 v[68:69], v5 offset0:198 offset1:231
	ds_read2_b32 v[70:71], v5 offset0:8 offset1:41
	ds_read2_b32 v[72:73], v5 offset0:74 offset1:107
	ds_read2_b32 v[162:163], v5 offset0:140 offset1:173
	ds_read2_b32 v[164:165], v5 offset0:206 offset1:239
	s_add_u32 s7, s10, 0x200000
	s_waitcnt lgkmcnt(7)
	v_cvt_pk_bf16_f32 v14, v62, v63
	ds_read2_b32 v[62:63], v5 offset0:16 offset1:49
	s_waitcnt lgkmcnt(7)
	v_cvt_pk_bf16_f32 v15, v64, v65
	ds_read2_b32 v[64:65], v5 offset0:82 offset1:115
	s_addc_u32 s6, s11, 0
	s_ashr_i32 s5, s4, 31
	s_lshl_b64 s[4:5], s[4:5], 1
	s_waitcnt lgkmcnt(7)
	v_cvt_pk_bf16_f32 v16, v66, v67
	ds_read2_b32 v[66:67], v5 offset0:148 offset1:181
	s_add_u32 s4, s7, s4
	s_waitcnt lgkmcnt(7)
	v_cvt_pk_bf16_f32 v17, v68, v69
	ds_read2_b32 v[68:69], v5 offset0:214 offset1:247
	v_or_b32_e32 v18, s12, v7
	v_mov_b32_e32 v9, 0
	v_lshlrev_b32_e32 v8, 1, v10
	s_addc_u32 s5, s6, s5
	v_ashrrev_i32_e32 v19, 31, v18
	v_lshl_add_u64 v[20:21], s[4:5], 0, v[8:9]
	v_lshlrev_b64 v[18:19], 11, v[18:19]
	v_lshl_add_u64 v[18:19], v[20:21], 0, v[18:19]
	global_store_dwordx4 v[18:19], v[14:17], off
	v_or_b32_e32 v13, 24, v7
	v_or_b32_e32 v26, s12, v13
	s_waitcnt lgkmcnt(7)
	v_cvt_pk_bf16_f32 v16, v70, v71
	ds_read2_b32 v[70:71], v5 offset0:24 offset1:57
	s_waitcnt lgkmcnt(7)
	v_cvt_pk_bf16_f32 v17, v72, v73
	ds_read2_b32 v[72:73], v5 offset0:90 offset1:123
	s_waitcnt lgkmcnt(7)
	v_cvt_pk_bf16_f32 v18, v162, v163
	ds_read2_b32 v[162:163], v5 offset0:156 offset1:189
	v_or_b32_e32 v15, 8, v7
	v_or_b32_e32 v24, s12, v15
	v_ashrrev_i32_e32 v25, 31, v24
	v_lshlrev_b64 v[24:25], 11, v[24:25]
	s_waitcnt lgkmcnt(7)
	v_cvt_pk_bf16_f32 v19, v164, v165
	ds_read2_b32 v[164:165], v5 offset0:222 offset1:255
	v_lshl_add_u64 v[24:25], v[20:21], 0, v[24:25]
	v_or_b32_e32 v14, 16, v7
	global_store_dwordx4 v[24:25], v[16:19], off
	v_or_b32_e32 v24, s12, v14
	v_ashrrev_i32_e32 v25, 31, v24
	s_waitcnt lgkmcnt(7)
	v_cvt_pk_bf16_f32 v16, v62, v63
	s_waitcnt lgkmcnt(6)
	v_cvt_pk_bf16_f32 v17, v64, v65
	s_waitcnt lgkmcnt(5)
	v_cvt_pk_bf16_f32 v18, v66, v67
	v_lshlrev_b64 v[24:25], 11, v[24:25]
	s_waitcnt lgkmcnt(4)
	v_cvt_pk_bf16_f32 v19, v68, v69
	v_ashrrev_i32_e32 v27, 31, v26
	v_lshl_add_u64 v[24:25], v[20:21], 0, v[24:25]
	global_store_dwordx4 v[24:25], v[16:19], off
	s_add_i32 s11, s13, 0xa00
	s_ashr_i32 s4, s11, 31
	s_waitcnt lgkmcnt(3)
	v_cvt_pk_bf16_f32 v16, v70, v71
	v_lshlrev_b64 v[22:23], 11, v[26:27]
	v_lshl_add_u64 v[20:21], v[20:21], 0, v[22:23]
	s_waitcnt lgkmcnt(2)
	v_cvt_pk_bf16_f32 v17, v72, v73
	s_lshr_b32 s4, s4, 28
	s_waitcnt lgkmcnt(1)
	v_cvt_pk_bf16_f32 v18, v162, v163
	s_waitcnt lgkmcnt(0)
	v_cvt_pk_bf16_f32 v19, v164, v165
	global_store_dwordx4 v[20:21], v[16:19], off
	s_add_i32 s4, s11, s4
	s_waitcnt lgkmcnt(0)
	s_ashr_i32 s12, s4, 4
	s_ashr_i32 s13, s4, 7
	s_lshl_b32 s10, s12, 5
	s_bfe_u32 s15, s12, 0x10002
	s_and_b32 s14, s12, 3
	s_and_b32 s4, s12, 0x7ffffc0
	s_cmp_lg_u32 s4, 64
	s_cbranch_scc0 .LBB0_62
	s_cmp_lt_i32 s13, 16
	s_cbranch_scc0 .LBB0_63
	s_lshl_b32 s4, s14, 6
	s_lshl_b32 s5, s15, 5
	s_or_b32 s4, s5, s4
	s_and_b32 s16, s10, 0xffffff00
	s_cmp_gt_i32 s13, 5
	v_or_b32_e32 v9, s4, v3
	s_cbranch_scc0 .LBB0_64
	v_add3_u32 v10, v9, s16, 8
	s_cbranch_execz .LBB0_65
	s_branch .LBB0_66

; #define LAS __attribute__((address_space(3)))
; template <bool MAP> __device__ __forceinline__ void p0_transpose_item(const float* W, int K, int NS, bf16* WT, LAS float* scr, int item, int nkb, int lane) {
;     const int pb = item / nkb, kb = item % nkb, k0 = 64 * kb, p0 = 32 * pb;
;     const int sc = MAP ? pg8::proj_src_col(p0 + (lane & 31)) : p0 + (lane & 31);
; #pragma unroll 8
;     for (int i = 0; i < 32; ++i) { const int kk = 2 * i + (lane >> 5); scr[kk * 33 + (lane & 31)] = W[(size_t)(k0 + kk) * NS + sc]; }
.LBB0_71:
	s_lshl_b32 s14, s8, 1
	s_lshl_b32 s15, s9, 1
	v_or_b32_e32 v9, s14, v1
	v_or_b32_e32 v12, s15, v4
	s_add_i32 s16, s14, 4
	s_add_i32 s17, s15, 4
	s_add_i32 s20, s14, 8
	s_add_i32 s21, s15, 8
	s_add_i32 s22, s14, 12
	s_add_i32 s23, s15, 12
	s_add_i32 s26, s14, 16
	s_add_i32 s27, s15, 16
	s_add_i32 s28, s14, 20
	s_add_i32 s29, s15, 20
	s_add_i32 s30, s14, 24
	s_add_i32 s31, s15, 24
	s_add_i32 s14, s14, 28
	s_add_i32 s15, s15, 28
	v_add_u32_e32 v10, s4, v12
	v_or_b32_e32 v46, s16, v1
	v_or_b32_e32 v47, s17, v4
	v_or_b32_e32 v48, s20, v1
	v_or_b32_e32 v49, s21, v4
	v_or_b32_e32 v50, s22, v1
	v_or_b32_e32 v51, s23, v4
	v_or_b32_e32 v52, s26, v1
	v_or_b32_e32 v53, s27, v4
	v_or_b32_e32 v54, s28, v1
	v_or_b32_e32 v55, s29, v4
	v_or_b32_e32 v56, s30, v1
	v_or_b32_e32 v57, s31, v4
	v_or_b32_e32 v58, s14, v1
	v_or_b32_e32 v59, s15, v4
	v_add_u32_e32 v11, s5, v9
	v_mul_lo_u32 v10, v10, s12
	v_add_u32_e32 v19, s5, v46
	v_add_u32_e32 v18, s4, v47
	v_add_u32_e32 v21, s5, v48
	v_add_u32_e32 v22, s4, v49
	v_add_u32_e32 v23, s5, v50
	v_add_u32_e32 v25, s4, v51
	v_add_u32_e32 v27, s5, v52
	v_add_u32_e32 v29, s4, v53
	v_add_u32_e32 v31, s5, v54
	v_add_u32_e32 v33, s4, v55
	v_add_u32_e32 v35, s5, v56
	v_add_u32_e32 v37, s4, v57
	v_add_u32_e32 v39, s5, v58
	v_add_u32_e32 v41, s4, v59
	v_mul_lo_u32 v16, v11, s12
	v_ashrrev_i32_e32 v11, 31, v10
	v_mul_lo_u32 v18, v18, s12
	v_mul_lo_u32 v20, v19, s12
	v_mul_lo_u32 v22, v22, s12
	v_mul_lo_u32 v24, v21, s12
	v_mul_lo_u32 v26, v25, s12
	v_mul_lo_u32 v28, v23, s12
	v_mul_lo_u32 v30, v29, s12
	v_mul_lo_u32 v32, v27, s12
	v_mul_lo_u32 v34, v33, s12
	v_mul_lo_u32 v36, v31, s12
	v_mul_lo_u32 v38, v37, s12
	v_mul_lo_u32 v40, v35, s12
	v_mul_lo_u32 v42, v41, s12
	v_mul_lo_u32 v44, v39, s12
	v_ashrrev_i32_e32 v17, 31, v16
	v_lshl_add_u64 v[10:11], v[10:11], 2, v[2:3]
	v_ashrrev_i32_e32 v21, 31, v20
	v_ashrrev_i32_e32 v19, 31, v18
	v_ashrrev_i32_e32 v25, 31, v24
	v_ashrrev_i32_e32 v23, 31, v22
	v_ashrrev_i32_e32 v29, 31, v28
	v_ashrrev_i32_e32 v27, 31, v26
	v_ashrrev_i32_e32 v33, 31, v32
	v_ashrrev_i32_e32 v31, 31, v30
	v_ashrrev_i32_e32 v37, 31, v36
	v_ashrrev_i32_e32 v35, 31, v34
	v_ashrrev_i32_e32 v41, 31, v40
	v_ashrrev_i32_e32 v39, 31, v38
	v_ashrrev_i32_e32 v45, 31, v44
	v_ashrrev_i32_e32 v43, 31, v42
	v_lshl_add_u64 v[16:17], v[16:17], 2, v[2:3]
	v_lshl_add_u64 v[18:19], v[18:19], 2, v[2:3]
	v_lshl_add_u64 v[20:21], v[20:21], 2, v[2:3]
	v_lshl_add_u64 v[22:23], v[22:23], 2, v[2:3]
	v_lshl_add_u64 v[24:25], v[24:25], 2, v[2:3]
	v_lshl_add_u64 v[26:27], v[26:27], 2, v[2:3]
	v_lshl_add_u64 v[28:29], v[28:29], 2, v[2:3]
	v_lshl_add_u64 v[30:31], v[30:31], 2, v[2:3]
	v_lshl_add_u64 v[32:33], v[32:33], 2, v[2:3]
	v_lshl_add_u64 v[34:35], v[34:35], 2, v[2:3]
	v_lshl_add_u64 v[36:37], v[36:37], 2, v[2:3]
	v_lshl_add_u64 v[38:39], v[38:39], 2, v[2:3]
	v_lshl_add_u64 v[40:41], v[40:41], 2, v[2:3]
	v_lshl_add_u64 v[42:43], v[42:43], 2, v[2:3]
	v_lshl_add_u64 v[44:45], v[44:45], 2, v[2:3]
	global_load_dword v60, v[10:11], off
	global_load_dword v61, v[16:17], off
	global_load_dword v62, v[18:19], off
	global_load_dword v63, v[20:21], off
	global_load_dword v64, v[22:23], off
	global_load_dword v65, v[24:25], off
	global_load_dword v66, v[26:27], off
	global_load_dword v67, v[28:29], off
	global_load_dword v68, v[30:31], off
	global_load_dword v69, v[32:33], off
	global_load_dword v70, v[34:35], off
	global_load_dword v71, v[36:37], off
	global_load_dword v72, v[38:39], off
	global_load_dword v73, v[40:41], off
	global_load_dword v74, v[42:43], off
	global_load_dword v75, v[44:45], off
	s_add_i32 s9, s9, 16
	s_add_i32 s8, s8, 16
	s_add_i32 s11, s11, -16
	v_mad_u64_u32 v[10:11], s[14:15], v12, s13, v[6:7]
	s_cmp_lg_u32 s11, 0
	v_mad_u64_u32 v[16:17], s[14:15], v9, s13, v[6:7]
	v_mad_u64_u32 v[18:19], s[14:15], v47, s13, v[6:7]
	v_mad_u64_u32 v[20:21], s[14:15], v46, s13, v[6:7]
	v_mad_u64_u32 v[22:23], s[14:15], v49, s13, v[6:7]
	v_mad_u64_u32 v[24:25], s[14:15], v48, s13, v[6:7]
	v_mad_u64_u32 v[26:27], s[14:15], v51, s13, v[6:7]
	v_mad_u64_u32 v[28:29], s[14:15], v50, s13, v[6:7]
	v_mad_u64_u32 v[30:31], s[14:15], v53, s13, v[6:7]
	v_mad_u64_u32 v[32:33], s[14:15], v52, s13, v[6:7]
	v_mad_u64_u32 v[34:35], s[14:15], v55, s13, v[6:7]
	v_mad_u64_u32 v[36:37], s[14:15], v54, s13, v[6:7]
	v_mad_u64_u32 v[38:39], s[14:15], v57, s13, v[6:7]
	v_mad_u64_u32 v[40:41], s[14:15], v56, s13, v[6:7]
	v_mad_u64_u32 v[42:43], s[14:15], v59, s13, v[6:7]
	v_mad_u64_u32 v[44:45], s[14:15], v58, s13, v[6:7]
	s_lshl_b32 s14, s8, 1
	s_lshl_b32 s15, s9, 1
	v_or_b32_e32 v109, s14, v1
	v_or_b32_e32 v112, s15, v4
	s_add_i32 s16, s14, 4
	s_add_i32 s17, s15, 4
	s_add_i32 s20, s14, 8
	s_add_i32 s21, s15, 8
	s_add_i32 s22, s14, 12
	s_add_i32 s23, s15, 12
	s_add_i32 s26, s14, 16
	s_add_i32 s27, s15, 16
	s_add_i32 s28, s14, 20
	s_add_i32 s29, s15, 20
	s_add_i32 s30, s14, 24
	s_add_i32 s31, s15, 24
	s_add_i32 s14, s14, 28
	s_add_i32 s15, s15, 28
	v_add_u32_e32 v110, s4, v112
	v_or_b32_e32 v146, s16, v1
	v_or_b32_e32 v147, s17, v4
	v_or_b32_e32 v148, s20, v1
	v_or_b32_e32 v149, s21, v4
	v_or_b32_e32 v150, s22, v1
	v_or_b32_e32 v151, s23, v4
	v_or_b32_e32 v152, s26, v1
	v_or_b32_e32 v153, s27, v4
	v_or_b32_e32 v154, s28, v1
	v_or_b32_e32 v155, s29, v4
	v_or_b32_e32 v156, s30, v1
	v_or_b32_e32 v157, s31, v4
	v_or_b32_e32 v158, s14, v1
	v_or_b32_e32 v159, s15, v4
	v_add_u32_e32 v111, s5, v109
	v_mul_lo_u32 v110, v110, s12
	v_add_u32_e32 v119, s5, v146
	v_add_u32_e32 v118, s4, v147
	v_add_u32_e32 v121, s5, v148
	v_add_u32_e32 v122, s4, v149
	v_add_u32_e32 v123, s5, v150
	v_add_u32_e32 v125, s4, v151
	v_add_u32_e32 v127, s5, v152
	v_add_u32_e32 v129, s4, v153
; template <bool MAP> __device__ __forceinline__ void p0_transpose_item(const float* W, int K, int NS, bf16* WT, LAS float* scr, int item, int nkb, int lane) {
;     ...
;     for (int i = 0; i < 32; ++i) { const int kk = 2 * i + (lane >> 5); scr[kk * 33 + (lane & 31)] = W[(size_t)(k0 + kk) * NS + sc]; }
	v_add_u32_e32 v131, s5, v154
	v_add_u32_e32 v133, s4, v155
	v_add_u32_e32 v135, s5, v156
	v_add_u32_e32 v137, s4, v157
	v_add_u32_e32 v139, s5, v158
	v_add_u32_e32 v141, s4, v159
	v_mul_lo_u32 v116, v111, s12
	v_ashrrev_i32_e32 v111, 31, v110
	v_mul_lo_u32 v118, v118, s12
	v_mul_lo_u32 v120, v119, s12
	v_mul_lo_u32 v122, v122, s12
	v_mul_lo_u32 v124, v121, s12
	v_mul_lo_u32 v126, v125, s12
	v_mul_lo_u32 v128, v123, s12
	v_mul_lo_u32 v130, v129, s12
	v_mul_lo_u32 v132, v127, s12
	v_mul_lo_u32 v134, v133, s12
	v_mul_lo_u32 v136, v131, s12
	v_mul_lo_u32 v138, v137, s12
	v_mul_lo_u32 v140, v135, s12
	v_mul_lo_u32 v142, v141, s12
	v_mul_lo_u32 v144, v139, s12
	v_ashrrev_i32_e32 v117, 31, v116
	v_lshl_add_u64 v[110:111], v[110:111], 2, v[2:3]
	v_ashrrev_i32_e32 v121, 31, v120
	v_ashrrev_i32_e32 v119, 31, v118
	v_ashrrev_i32_e32 v125, 31, v124
	v_ashrrev_i32_e32 v123, 31, v122
	v_ashrrev_i32_e32 v129, 31, v128
	v_ashrrev_i32_e32 v127, 31, v126
	v_ashrrev_i32_e32 v133, 31, v132
	v_ashrrev_i32_e32 v131, 31, v130
	v_ashrrev_i32_e32 v137, 31, v136
	v_ashrrev_i32_e32 v135, 31, v134
	v_ashrrev_i32_e32 v141, 31, v140
	v_ashrrev_i32_e32 v139, 31, v138
	v_ashrrev_i32_e32 v145, 31, v144
	v_ashrrev_i32_e32 v143, 31, v142
	v_lshl_add_u64 v[116:117], v[116:117], 2, v[2:3]
	v_lshl_add_u64 v[118:119], v[118:119], 2, v[2:3]
	v_lshl_add_u64 v[120:121], v[120:121], 2, v[2:3]
	v_lshl_add_u64 v[122:123], v[122:123], 2, v[2:3]
	v_lshl_add_u64 v[124:125], v[124:125], 2, v[2:3]
	v_lshl_add_u64 v[126:127], v[126:127], 2, v[2:3]
	v_lshl_add_u64 v[128:129], v[128:129], 2, v[2:3]
	v_lshl_add_u64 v[130:131], v[130:131], 2, v[2:3]
	v_lshl_add_u64 v[132:133], v[132:133], 2, v[2:3]
	v_lshl_add_u64 v[134:135], v[134:135], 2, v[2:3]
	v_lshl_add_u64 v[136:137], v[136:137], 2, v[2:3]
	v_lshl_add_u64 v[138:139], v[138:139], 2, v[2:3]
	v_lshl_add_u64 v[140:141], v[140:141], 2, v[2:3]
	v_lshl_add_u64 v[142:143], v[142:143], 2, v[2:3]
	v_lshl_add_u64 v[144:145], v[144:145], 2, v[2:3]
	global_load_dword v160, v[110:111], off
	global_load_dword v161, v[116:117], off
	global_load_dword v162, v[118:119], off
	global_load_dword v163, v[120:121], off
	global_load_dword v164, v[122:123], off
	global_load_dword v165, v[124:125], off
	global_load_dword v166, v[126:127], off
	global_load_dword v167, v[128:129], off
	global_load_dword v168, v[130:131], off
	global_load_dword v169, v[132:133], off
	global_load_dword v170, v[134:135], off
	global_load_dword v171, v[136:137], off
	global_load_dword v172, v[138:139], off
	global_load_dword v173, v[140:141], off
	global_load_dword v174, v[142:143], off
	global_load_dword v175, v[144:145], off
	s_waitcnt vmcnt(31)
	ds_write_b32 v10, v60
	s_waitcnt vmcnt(30)
	ds_write_b32 v16, v61
	s_waitcnt vmcnt(29)
	ds_write_b32 v18, v62
	s_waitcnt vmcnt(28)
	ds_write_b32 v20, v63
	s_waitcnt vmcnt(27)
	ds_write_b32 v22, v64
	s_waitcnt vmcnt(26)
	ds_write_b32 v24, v65
	s_waitcnt vmcnt(25)
	ds_write_b32 v26, v66
	s_waitcnt vmcnt(24)
	ds_write_b32 v28, v67
	s_waitcnt vmcnt(23)
	ds_write_b32 v30, v68
	s_waitcnt vmcnt(22)
	ds_write_b32 v32, v69
	s_waitcnt vmcnt(21)
	ds_write_b32 v34, v70
	s_waitcnt vmcnt(20)
	ds_write_b32 v36, v71
	s_waitcnt vmcnt(19)
	ds_write_b32 v38, v72
	s_waitcnt vmcnt(18)
	ds_write_b32 v40, v73
	s_waitcnt vmcnt(17)
	ds_write_b32 v42, v74
	s_waitcnt vmcnt(16)
; #define GAS __attribute__((address_space(1)))
; #define LAS __attribute__((address_space(3)))
; #define LDS_WAIT() asm volatile("s_waitcnt lgkmcnt(0)" ::: "memory")
; __device__ __forceinline__ unsigned pk2(float lo, float hi) { return pg8::cvt_pk_bf16(lo, hi); }
; template <bool MAP> __device__ __forceinline__ void p0_transpose_item(const float* W, int K, int NS, bf16* WT, LAS float* scr, int item, int nkb, int lane) {
;     ...
;     for (int i = 0; i < 32; ++i) { const int kk = 2 * i + (lane >> 5); scr[kk * 33 + (lane & 31)] = W[(size_t)(k0 + kk) * NS + sc]; }
;     LDS_WAIT(); asm volatile("" ::: "memory");
;     const int c = lane & 7;
; #pragma unroll
;     for (int j = 0; j < 4; ++j) { const int n = (lane >> 3) + 8 * j; const LAS float* s = scr + (8 * c) * 33 + n;
;         v4u o; o.x = pk2(s[0 * 33], s[1 * 33]); o.y = pk2(s[2 * 33], s[3 * 33]); o.z = pk2(s[4 * 33], s[5 * 33]); o.w = pk2(s[6 * 33], s[7 * 33]);
;         *(GAS v4u*)(WT + (size_t)(p0 + n) * K + k0 + 8 * c) = o; }
;     LDS_WAIT(); asm volatile("" ::: "memory");
	ds_write_b32 v44, v75
	s_add_i32 s9, s9, 16
	s_add_i32 s8, s8, 16
	s_add_i32 s11, s11, -16
	v_mad_u64_u32 v[10:11], s[14:15], v112, s13, v[6:7]
	s_cmp_lg_u32 s11, 0
	v_mad_u64_u32 v[16:17], s[14:15], v109, s13, v[6:7]
	v_mad_u64_u32 v[18:19], s[14:15], v147, s13, v[6:7]
	v_mad_u64_u32 v[20:21], s[14:15], v146, s13, v[6:7]
	v_mad_u64_u32 v[22:23], s[14:15], v149, s13, v[6:7]
	v_mad_u64_u32 v[24:25], s[14:15], v148, s13, v[6:7]
	v_mad_u64_u32 v[26:27], s[14:15], v151, s13, v[6:7]
	v_mad_u64_u32 v[28:29], s[14:15], v150, s13, v[6:7]
	v_mad_u64_u32 v[30:31], s[14:15], v153, s13, v[6:7]
	v_mad_u64_u32 v[32:33], s[14:15], v152, s13, v[6:7]
	v_mad_u64_u32 v[34:35], s[14:15], v155, s13, v[6:7]
	v_mad_u64_u32 v[36:37], s[14:15], v154, s13, v[6:7]
	v_mad_u64_u32 v[38:39], s[14:15], v157, s13, v[6:7]
	v_mad_u64_u32 v[40:41], s[14:15], v156, s13, v[6:7]
	v_mad_u64_u32 v[42:43], s[14:15], v159, s13, v[6:7]
	v_mad_u64_u32 v[44:45], s[14:15], v158, s13, v[6:7]
	s_waitcnt vmcnt(15)
	ds_write_b32 v10, v160
	s_waitcnt vmcnt(14)
	ds_write_b32 v16, v161
	s_waitcnt vmcnt(13)
	ds_write_b32 v18, v162
	s_waitcnt vmcnt(12)
	ds_write_b32 v20, v163
	s_waitcnt vmcnt(11)
	ds_write_b32 v22, v164
	s_waitcnt vmcnt(10)
	ds_write_b32 v24, v165
	s_waitcnt vmcnt(9)
	ds_write_b32 v26, v166
	s_waitcnt vmcnt(8)
	ds_write_b32 v28, v167
	s_waitcnt vmcnt(7)
	ds_write_b32 v30, v168
	s_waitcnt vmcnt(6)
	ds_write_b32 v32, v169
	s_waitcnt vmcnt(5)
	ds_write_b32 v34, v170
	s_waitcnt vmcnt(4)
	ds_write_b32 v36, v171
	s_waitcnt vmcnt(3)
	ds_write_b32 v38, v172
	s_waitcnt vmcnt(2)
	ds_write_b32 v40, v173
	s_waitcnt vmcnt(1)
	ds_write_b32 v42, v174
	s_waitcnt vmcnt(0)
	ds_write_b32 v44, v175
	s_waitcnt lgkmcnt(0)
	s_ashr_i32 s5, s4, 31
	ds_read2_b32 v[60:61], v5 offset1:33
	ds_read2_b32 v[62:63], v5 offset0:66 offset1:99
	ds_read2_b32 v[64:65], v5 offset0:132 offset1:165
	ds_read2_b32 v[66:67], v5 offset0:198 offset1:231
	ds_read2_b32 v[68:69], v5 offset0:8 offset1:41
	ds_read2_b32 v[70:71], v5 offset0:74 offset1:107
	ds_read2_b32 v[72:73], v5 offset0:140 offset1:173
	ds_read2_b32 v[74:75], v5 offset0:206 offset1:239
	s_lshl_b64 s[4:5], s[4:5], 1
	s_waitcnt lgkmcnt(7)
	v_cvt_pk_bf16_f32 v16, v60, v61
	ds_read2_b32 v[60:61], v5 offset0:16 offset1:49
	v_or_b32_e32 v6, s10, v7
	s_add_u32 s4, s7, s4
	s_waitcnt lgkmcnt(7)
	v_cvt_pk_bf16_f32 v17, v62, v63
	ds_read2_b32 v[62:63], v5 offset0:82 offset1:115
	v_mov_b32_e32 v9, 0
	v_ashrrev_i32_e32 v7, 31, v6
	s_addc_u32 s5, s6, s5
	s_waitcnt lgkmcnt(7)
	v_cvt_pk_bf16_f32 v18, v64, v65
	ds_read2_b32 v[64:65], v5 offset0:148 offset1:181
	v_lshlrev_b64 v[6:7], 11, v[6:7]
	v_lshl_add_u64 v[10:11], s[4:5], 0, v[8:9]
	s_waitcnt lgkmcnt(7)
	v_cvt_pk_bf16_f32 v19, v66, v67
	ds_read2_b32 v[66:67], v5 offset0:214 offset1:247
	v_lshl_add_u64 v[6:7], v[10:11], 0, v[6:7]
	global_store_dwordx4 v[6:7], v[16:19], off
	s_waitcnt lgkmcnt(7)
	v_cvt_pk_bf16_f32 v6, v68, v69
	ds_read2_b32 v[68:69], v5 offset0:24 offset1:57
	s_waitcnt lgkmcnt(7)
	v_cvt_pk_bf16_f32 v7, v70, v71
	ds_read2_b32 v[70:71], v5 offset0:90 offset1:123
	v_or_b32_e32 v16, s10, v15
	v_ashrrev_i32_e32 v17, 31, v16
	s_waitcnt lgkmcnt(7)
	v_cvt_pk_bf16_f32 v8, v72, v73
	ds_read2_b32 v[72:73], v5 offset0:156 offset1:189
	v_lshlrev_b64 v[16:17], 11, v[16:17]
	s_waitcnt lgkmcnt(7)
	v_cvt_pk_bf16_f32 v9, v74, v75
	ds_read2_b32 v[74:75], v5 offset0:222 offset1:255
	v_lshl_add_u64 v[16:17], v[10:11], 0, v[16:17]
	global_store_dwordx4 v[16:17], v[6:9], off
	v_or_b32_e32 v14, s10, v14
	v_ashrrev_i32_e32 v15, 31, v14
	s_waitcnt lgkmcnt(7)
	v_cvt_pk_bf16_f32 v6, v60, v61
	s_waitcnt lgkmcnt(6)
	v_cvt_pk_bf16_f32 v7, v62, v63
	s_waitcnt lgkmcnt(5)
	v_cvt_pk_bf16_f32 v8, v64, v65
	v_lshlrev_b64 v[14:15], 11, v[14:15]
	s_waitcnt lgkmcnt(4)
	v_cvt_pk_bf16_f32 v9, v66, v67
	v_lshl_add_u64 v[14:15], v[10:11], 0, v[14:15]
	global_store_dwordx4 v[14:15], v[6:9], off
	s_waitcnt lgkmcnt(3)
	v_cvt_pk_bf16_f32 v2, v68, v69
	s_waitcnt lgkmcnt(2)
	v_cvt_pk_bf16_f32 v3, v70, v71
	v_or_b32_e32 v8, s10, v13
	v_ashrrev_i32_e32 v9, 31, v8
	s_waitcnt lgkmcnt(1)
	v_cvt_pk_bf16_f32 v4, v72, v73
	v_lshlrev_b64 v[8:9], 11, v[8:9]
	s_waitcnt lgkmcnt(0)
	v_cvt_pk_bf16_f32 v5, v74, v75
	v_lshl_add_u64 v[6:7], v[10:11], 0, v[8:9]
	global_store_dwordx4 v[6:7], v[2:5], off
	s_waitcnt lgkmcnt(0)

; template <bool MAP> __device__ __forceinline__ void p0_transpose_item(const float* W, int K, int NS, bf16* WT, LAS float* scr, int item, int nkb, int lane) {
;     ...
;     for (int i = 0; i < 32; ++i) { const int kk = 2 * i + (lane >> 5); scr[kk * 33 + (lane & 31)] = W[(size_t)(k0 + kk) * NS + sc]; }
; template <int LO, int HI> __global__ void __launch_bounds__(NWAVES * 64, 2) fox_fwd(Args args) {
;     ...
;             for (int it = gw; it < 2048; it += NGW) p0_transpose_item<true>(w_in, D, INW, W1T, scr, it, D / 64, lane);
.LBB0_145:
	s_lshl_b32 s13, s10, 1
	s_lshl_b32 s14, s11, 1
	v_or_b32_e32 v17, s13, v1
	v_or_b32_e32 v34, s14, v2
	s_add_i32 s15, s13, 4
	s_add_i32 s16, s14, 4
	s_add_i32 s17, s13, 8
	s_add_i32 s20, s14, 8
	s_add_i32 s21, s13, 12
	s_add_i32 s26, s14, 12
	s_add_i32 s27, s13, 16
	s_add_i32 s28, s14, 16
	s_add_i32 s29, s13, 20
	s_add_i32 s30, s14, 20
	s_add_i32 s31, s13, 24
	s_add_i32 s34, s14, 24
	s_add_i32 s13, s13, 28
	s_add_i32 s14, s14, 28
	v_add_u32_e32 v18, s4, v34
	v_or_b32_e32 v52, s15, v1
	v_or_b32_e32 v53, s16, v2
	v_or_b32_e32 v54, s17, v1
	v_or_b32_e32 v55, s20, v2
	v_or_b32_e32 v56, s21, v1
	v_or_b32_e32 v57, s26, v2
	v_or_b32_e32 v58, s27, v1
	v_or_b32_e32 v59, s28, v2
	v_or_b32_e32 v60, s29, v1
	v_or_b32_e32 v61, s30, v2
	v_or_b32_e32 v62, s31, v1
	v_or_b32_e32 v63, s34, v2
	v_or_b32_e32 v64, s13, v1
	v_or_b32_e32 v65, s14, v2
	v_add_u32_e32 v19, s5, v17
	v_mul_lo_u32 v18, v18, s8
	v_add_u32_e32 v23, s5, v52
	v_add_u32_e32 v22, s4, v53
	v_add_u32_e32 v25, s5, v54
	v_add_u32_e32 v26, s4, v55
	v_add_u32_e32 v27, s5, v56
	v_add_u32_e32 v29, s4, v57
	v_add_u32_e32 v31, s5, v58
	v_add_u32_e32 v33, s4, v59
	v_add_u32_e32 v37, s5, v60
	v_add_u32_e32 v39, s4, v61
	v_add_u32_e32 v41, s5, v62
	v_add_u32_e32 v43, s4, v63
	v_add_u32_e32 v45, s5, v64
	v_add_u32_e32 v47, s4, v65
	v_mul_lo_u32 v20, v19, s8
	v_ashrrev_i32_e32 v19, 31, v18
	v_mul_lo_u32 v22, v22, s8
	v_mul_lo_u32 v24, v23, s8
	v_mul_lo_u32 v26, v26, s8
	v_mul_lo_u32 v28, v25, s8
	v_mul_lo_u32 v30, v29, s8
	v_mul_lo_u32 v32, v27, s8
	v_mul_lo_u32 v36, v33, s8
	v_mul_lo_u32 v38, v31, s8
	v_mul_lo_u32 v40, v39, s8
	v_mul_lo_u32 v42, v37, s8
	v_mul_lo_u32 v44, v43, s8
	v_mul_lo_u32 v46, v41, s8
	v_mul_lo_u32 v48, v47, s8
	v_mul_lo_u32 v50, v45, s8
	v_ashrrev_i32_e32 v21, 31, v20
	v_lshl_add_u64 v[18:19], v[18:19], 2, v[8:9]
	v_ashrrev_i32_e32 v25, 31, v24
	v_ashrrev_i32_e32 v23, 31, v22
	v_ashrrev_i32_e32 v29, 31, v28
	v_ashrrev_i32_e32 v27, 31, v26
	v_ashrrev_i32_e32 v33, 31, v32
	v_ashrrev_i32_e32 v31, 31, v30
	v_ashrrev_i32_e32 v39, 31, v38
	v_ashrrev_i32_e32 v37, 31, v36
	v_ashrrev_i32_e32 v43, 31, v42
	v_ashrrev_i32_e32 v41, 31, v40
	v_ashrrev_i32_e32 v47, 31, v46
	v_ashrrev_i32_e32 v45, 31, v44
	v_ashrrev_i32_e32 v51, 31, v50
	v_ashrrev_i32_e32 v49, 31, v48
	v_lshl_add_u64 v[20:21], v[20:21], 2, v[8:9]
	v_lshl_add_u64 v[22:23], v[22:23], 2, v[8:9]
	v_lshl_add_u64 v[24:25], v[24:25], 2, v[8:9]
	v_lshl_add_u64 v[26:27], v[26:27], 2, v[8:9]
	v_lshl_add_u64 v[28:29], v[28:29], 2, v[8:9]
	v_lshl_add_u64 v[30:31], v[30:31], 2, v[8:9]
	v_lshl_add_u64 v[32:33], v[32:33], 2, v[8:9]
	v_lshl_add_u64 v[36:37], v[36:37], 2, v[8:9]
	v_lshl_add_u64 v[38:39], v[38:39], 2, v[8:9]
	v_lshl_add_u64 v[40:41], v[40:41], 2, v[8:9]
	v_lshl_add_u64 v[42:43], v[42:43], 2, v[8:9]
	v_lshl_add_u64 v[44:45], v[44:45], 2, v[8:9]
	v_lshl_add_u64 v[46:47], v[46:47], 2, v[8:9]
	v_lshl_add_u64 v[48:49], v[48:49], 2, v[8:9]
	v_lshl_add_u64 v[50:51], v[50:51], 2, v[8:9]
	global_load_dword v66, v[18:19], off
	global_load_dword v67, v[20:21], off
	global_load_dword v69, v[22:23], off
	global_load_dword v70, v[24:25], off
	global_load_dword v71, v[26:27], off
	global_load_dword v72, v[28:29], off
	global_load_dword v73, v[30:31], off
	global_load_dword v74, v[32:33], off
	global_load_dword v75, v[36:37], off
	global_load_dword v76, v[38:39], off
	global_load_dword v77, v[40:41], off
	global_load_dword v78, v[42:43], off
	global_load_dword v79, v[44:45], off
	global_load_dword v80, v[46:47], off
	global_load_dword v81, v[48:49], off
	global_load_dword v82, v[50:51], off
	s_add_i32 s11, s11, 16
	s_add_i32 s10, s10, 16
	s_add_i32 s12, s12, -16
	v_mad_u64_u32 v[18:19], s[14:15], v34, s7, v[4:5]
	s_cmp_lg_u32 s12, 0
	v_mad_u64_u32 v[20:21], s[14:15], v17, s7, v[4:5]
	v_mad_u64_u32 v[22:23], s[14:15], v53, s7, v[4:5]
	v_mad_u64_u32 v[24:25], s[14:15], v52, s7, v[4:5]
	v_mad_u64_u32 v[26:27], s[14:15], v55, s7, v[4:5]
	v_mad_u64_u32 v[28:29], s[14:15], v54, s7, v[4:5]
	v_mad_u64_u32 v[30:31], s[14:15], v57, s7, v[4:5]
	v_mad_u64_u32 v[32:33], s[14:15], v56, s7, v[4:5]
	v_mad_u64_u32 v[36:37], s[14:15], v59, s7, v[4:5]
	v_mad_u64_u32 v[38:39], s[14:15], v58, s7, v[4:5]
	v_mad_u64_u32 v[40:41], s[14:15], v61, s7, v[4:5]
	v_mad_u64_u32 v[42:43], s[14:15], v60, s7, v[4:5]
	v_mad_u64_u32 v[44:45], s[14:15], v63, s7, v[4:5]
	v_mad_u64_u32 v[46:47], s[14:15], v62, s7, v[4:5]
	v_mad_u64_u32 v[48:49], s[14:15], v65, s7, v[4:5]
	v_mad_u64_u32 v[50:51], s[14:15], v64, s7, v[4:5]
	s_lshl_b32 s13, s10, 1
	s_lshl_b32 s14, s11, 1
	v_or_b32_e32 v187, s13, v1
	v_or_b32_e32 v204, s14, v2
	s_add_i32 s15, s13, 4
	s_add_i32 s16, s14, 4
	s_add_i32 s17, s13, 8
	s_add_i32 s20, s14, 8
	s_add_i32 s21, s13, 12
	s_add_i32 s26, s14, 12
	s_add_i32 s27, s13, 16
	s_add_i32 s28, s14, 16
	s_add_i32 s29, s13, 20
	s_add_i32 s30, s14, 20
	s_add_i32 s31, s13, 24
	s_add_i32 s34, s14, 24
	s_add_i32 s13, s13, 28
	s_add_i32 s14, s14, 28
	v_add_u32_e32 v188, s4, v204
	v_or_b32_e32 v222, s15, v1
	v_or_b32_e32 v223, s16, v2
	v_or_b32_e32 v224, s17, v1
	v_or_b32_e32 v225, s20, v2
	v_or_b32_e32 v226, s21, v1
	v_or_b32_e32 v227, s26, v2
	v_or_b32_e32 v228, s27, v1
	v_or_b32_e32 v229, s28, v2
	v_or_b32_e32 v230, s29, v1
	v_or_b32_e32 v231, s30, v2
	v_or_b32_e32 v232, s31, v1
	v_or_b32_e32 v233, s34, v2
	v_or_b32_e32 v234, s13, v1
	v_or_b32_e32 v235, s14, v2
	v_add_u32_e32 v189, s5, v187
	v_mul_lo_u32 v188, v188, s8
	v_add_u32_e32 v193, s5, v222
	v_add_u32_e32 v192, s4, v223
	v_add_u32_e32 v195, s5, v224
	v_add_u32_e32 v196, s4, v225
	v_add_u32_e32 v197, s5, v226
	v_add_u32_e32 v199, s4, v227
	v_add_u32_e32 v201, s5, v228
	v_add_u32_e32 v203, s4, v229
; template <bool MAP> __device__ __forceinline__ void p0_transpose_item(const float* W, int K, int NS, bf16* WT, LAS float* scr, int item, int nkb, int lane) {
;     ...
;     for (int i = 0; i < 32; ++i) { const int kk = 2 * i + (lane >> 5); scr[kk * 33 + (lane & 31)] = W[(size_t)(k0 + kk) * NS + sc]; }
	v_add_u32_e32 v207, s5, v230
	v_add_u32_e32 v209, s4, v231
	v_add_u32_e32 v211, s5, v232
	v_add_u32_e32 v213, s4, v233
	v_add_u32_e32 v215, s5, v234
	v_add_u32_e32 v217, s4, v235
	v_mul_lo_u32 v190, v189, s8
	v_ashrrev_i32_e32 v189, 31, v188
	v_mul_lo_u32 v192, v192, s8
	v_mul_lo_u32 v194, v193, s8
	v_mul_lo_u32 v196, v196, s8
	v_mul_lo_u32 v198, v195, s8
	v_mul_lo_u32 v200, v199, s8
	v_mul_lo_u32 v202, v197, s8
	v_mul_lo_u32 v206, v203, s8
	v_mul_lo_u32 v208, v201, s8
	v_mul_lo_u32 v210, v209, s8
	v_mul_lo_u32 v212, v207, s8
	v_mul_lo_u32 v214, v213, s8
	v_mul_lo_u32 v216, v211, s8
	v_mul_lo_u32 v218, v217, s8
	v_mul_lo_u32 v220, v215, s8
	v_ashrrev_i32_e32 v191, 31, v190
	v_lshl_add_u64 v[188:189], v[188:189], 2, v[8:9]
	v_ashrrev_i32_e32 v195, 31, v194
	v_ashrrev_i32_e32 v193, 31, v192
	v_ashrrev_i32_e32 v199, 31, v198
	v_ashrrev_i32_e32 v197, 31, v196
	v_ashrrev_i32_e32 v203, 31, v202
	v_ashrrev_i32_e32 v201, 31, v200
	v_ashrrev_i32_e32 v209, 31, v208
	v_ashrrev_i32_e32 v207, 31, v206
	v_ashrrev_i32_e32 v213, 31, v212
	v_ashrrev_i32_e32 v211, 31, v210
	v_ashrrev_i32_e32 v217, 31, v216
	v_ashrrev_i32_e32 v215, 31, v214
	v_ashrrev_i32_e32 v221, 31, v220
	v_ashrrev_i32_e32 v219, 31, v218
	v_lshl_add_u64 v[190:191], v[190:191], 2, v[8:9]
	v_lshl_add_u64 v[192:193], v[192:193], 2, v[8:9]
	v_lshl_add_u64 v[194:195], v[194:195], 2, v[8:9]
	v_lshl_add_u64 v[196:197], v[196:197], 2, v[8:9]
	v_lshl_add_u64 v[198:199], v[198:199], 2, v[8:9]
	v_lshl_add_u64 v[200:201], v[200:201], 2, v[8:9]
	v_lshl_add_u64 v[202:203], v[202:203], 2, v[8:9]
	v_lshl_add_u64 v[206:207], v[206:207], 2, v[8:9]
	v_lshl_add_u64 v[208:209], v[208:209], 2, v[8:9]
	v_lshl_add_u64 v[210:211], v[210:211], 2, v[8:9]
	v_lshl_add_u64 v[212:213], v[212:213], 2, v[8:9]
	v_lshl_add_u64 v[214:215], v[214:215], 2, v[8:9]
	v_lshl_add_u64 v[216:217], v[216:217], 2, v[8:9]
	v_lshl_add_u64 v[218:219], v[218:219], 2, v[8:9]
	v_lshl_add_u64 v[220:221], v[220:221], 2, v[8:9]
	global_load_dword v236, v[188:189], off
	global_load_dword v237, v[190:191], off
	global_load_dword v239, v[192:193], off
	global_load_dword v240, v[194:195], off
	global_load_dword v241, v[196:197], off
	global_load_dword v242, v[198:199], off
	global_load_dword v243, v[200:201], off
	global_load_dword v244, v[202:203], off
	global_load_dword v245, v[206:207], off
	global_load_dword v246, v[208:209], off
	global_load_dword v247, v[210:211], off
	global_load_dword v248, v[212:213], off
	global_load_dword v249, v[214:215], off
	global_load_dword v250, v[216:217], off
	global_load_dword v251, v[218:219], off
	global_load_dword v252, v[220:221], off
	s_waitcnt vmcnt(31)
	ds_write_b32 v18, v66 offset:32768
	s_waitcnt vmcnt(30)
	ds_write_b32 v20, v67 offset:32768
	s_waitcnt vmcnt(29)
	ds_write_b32 v22, v69 offset:32768
	s_waitcnt vmcnt(28)
	ds_write_b32 v24, v70 offset:32768
	s_waitcnt vmcnt(27)
	ds_write_b32 v26, v71 offset:32768
	s_waitcnt vmcnt(26)
	ds_write_b32 v28, v72 offset:32768
	s_waitcnt vmcnt(25)
	ds_write_b32 v30, v73 offset:32768
	s_waitcnt vmcnt(24)
	ds_write_b32 v32, v74 offset:32768
	s_waitcnt vmcnt(23)
	ds_write_b32 v36, v75 offset:32768
	s_waitcnt vmcnt(22)
	ds_write_b32 v38, v76 offset:32768
	s_waitcnt vmcnt(21)
	ds_write_b32 v40, v77 offset:32768
	s_waitcnt vmcnt(20)
	ds_write_b32 v42, v78 offset:32768
	s_waitcnt vmcnt(19)
	ds_write_b32 v44, v79 offset:32768
	s_waitcnt vmcnt(18)
	ds_write_b32 v46, v80 offset:32768
	s_waitcnt vmcnt(17)
	ds_write_b32 v48, v81 offset:32768
	s_waitcnt vmcnt(16)
	ds_write_b32 v50, v82 offset:32768
	s_add_i32 s11, s11, 16
	s_add_i32 s10, s10, 16
	s_add_i32 s12, s12, -16
	v_mad_u64_u32 v[18:19], s[14:15], v204, s7, v[4:5]
	s_cmp_lg_u32 s12, 0
	v_mad_u64_u32 v[20:21], s[14:15], v187, s7, v[4:5]
	v_mad_u64_u32 v[22:23], s[14:15], v223, s7, v[4:5]
	v_mad_u64_u32 v[24:25], s[14:15], v222, s7, v[4:5]
	v_mad_u64_u32 v[26:27], s[14:15], v225, s7, v[4:5]
	v_mad_u64_u32 v[28:29], s[14:15], v224, s7, v[4:5]
	v_mad_u64_u32 v[30:31], s[14:15], v227, s7, v[4:5]
	v_mad_u64_u32 v[32:33], s[14:15], v226, s7, v[4:5]
	v_mad_u64_u32 v[36:37], s[14:15], v229, s7, v[4:5]
	v_mad_u64_u32 v[38:39], s[14:15], v228, s7, v[4:5]
	v_mad_u64_u32 v[40:41], s[14:15], v231, s7, v[4:5]
	v_mad_u64_u32 v[42:43], s[14:15], v230, s7, v[4:5]
	v_mad_u64_u32 v[44:45], s[14:15], v233, s7, v[4:5]
	v_mad_u64_u32 v[46:47], s[14:15], v232, s7, v[4:5]
	v_mad_u64_u32 v[48:49], s[14:15], v235, s7, v[4:5]
	v_mad_u64_u32 v[50:51], s[14:15], v234, s7, v[4:5]
	s_waitcnt vmcnt(15)
; #define GAS __attribute__((address_space(1)))
; #define LAS __attribute__((address_space(3)))
; #define LDS_WAIT() asm volatile("s_waitcnt lgkmcnt(0)" ::: "memory")
; __device__ __forceinline__ unsigned pk2(float lo, float hi) { return pg8::cvt_pk_bf16(lo, hi); }
; template <bool MAP> __device__ __forceinline__ void p0_transpose_item(const float* W, int K, int NS, bf16* WT, LAS float* scr, int item, int nkb, int lane) {
;     ...
;     const int c = lane & 7;
; #pragma unroll
;     for (int j = 0; j < 4; ++j) { const int n = (lane >> 3) + 8 * j; const LAS float* s = scr + (8 * c) * 33 + n;
;         v4u o; o.x = pk2(s[0 * 33], s[1 * 33]); o.y = pk2(s[2 * 33], s[3 * 33]); o.z = pk2(s[4 * 33], s[5 * 33]); o.w = pk2(s[6 * 33], s[7 * 33]);
;         *(GAS v4u*)(WT + (size_t)(p0 + n) * K + k0 + 8 * c) = o; }
;     LDS_WAIT(); asm volatile("" ::: "memory");
; template <int LO, int HI> __global__ void __launch_bounds__(NWAVES * 64, 2) fox_fwd(Args args) {
;     ...
;             for (int it = gw; it < 2048; it += NGW) p0_transpose_item<true>(w_in, D, INW, W1T, scr, it, D / 64, lane);
	ds_write_b32 v18, v236 offset:32768
	s_waitcnt vmcnt(14)
	ds_write_b32 v20, v237 offset:32768
	s_waitcnt vmcnt(13)
	ds_write_b32 v22, v239 offset:32768
	s_waitcnt vmcnt(12)
	ds_write_b32 v24, v240 offset:32768
	s_waitcnt vmcnt(11)
	ds_write_b32 v26, v241 offset:32768
	s_waitcnt vmcnt(10)
	ds_write_b32 v28, v242 offset:32768
	s_waitcnt vmcnt(9)
	ds_write_b32 v30, v243 offset:32768
	s_waitcnt vmcnt(8)
	ds_write_b32 v32, v244 offset:32768
	s_waitcnt vmcnt(7)
	ds_write_b32 v36, v245 offset:32768
	s_waitcnt vmcnt(6)
	ds_write_b32 v38, v246 offset:32768
	s_waitcnt vmcnt(5)
	ds_write_b32 v40, v247 offset:32768
	s_waitcnt vmcnt(4)
	ds_write_b32 v42, v248 offset:32768
	s_waitcnt vmcnt(3)
	ds_write_b32 v44, v249 offset:32768
	s_waitcnt vmcnt(2)
	ds_write_b32 v46, v250 offset:32768
	s_waitcnt vmcnt(1)
	ds_write_b32 v48, v251 offset:32768
	s_waitcnt vmcnt(0)
	ds_write_b32 v50, v252 offset:32768
	s_waitcnt lgkmcnt(0)
	v_add_u32_e32 v17, 0x8000, v13
	v_or_b32_e32 v22, s9, v12
	ds_read2_b32 v[66:67], v17 offset1:33
	ds_read2_b32 v[70:71], v17 offset0:66 offset1:99
	ds_read2_b32 v[72:73], v17 offset0:132 offset1:165
	ds_read2_b32 v[74:75], v17 offset0:198 offset1:231
	ds_read2_b32 v[76:77], v17 offset0:8 offset1:41
	ds_read2_b32 v[78:79], v17 offset0:74 offset1:107
	ds_read2_b32 v[80:81], v17 offset0:140 offset1:173
	ds_read2_b32 v[236:237], v17 offset0:206 offset1:239
	s_ashr_i32 s5, s4, 31
	v_ashrrev_i32_e32 v23, 31, v22
	s_waitcnt lgkmcnt(7)
	v_cvt_pk_bf16_f32 v18, v66, v67
	ds_read2_b32 v[66:67], v17 offset0:16 offset1:49
	v_lshl_add_u64 v[24:25], s[4:5], 1, v[6:7]
	v_lshlrev_b64 v[22:23], 11, v[22:23]
	s_waitcnt lgkmcnt(7)
	v_cvt_pk_bf16_f32 v19, v70, v71
	ds_read2_b32 v[70:71], v17 offset0:82 offset1:115
	v_lshl_add_u64 v[22:23], v[24:25], 0, v[22:23]
	s_waitcnt lgkmcnt(7)
	v_cvt_pk_bf16_f32 v20, v72, v73
	ds_read2_b32 v[72:73], v17 offset0:148 offset1:181
	s_waitcnt lgkmcnt(7)
	v_cvt_pk_bf16_f32 v21, v74, v75
	ds_read2_b32 v[74:75], v17 offset0:214 offset1:247
	global_store_dwordx4 v[22:23], v[18:21], off
	v_or_b32_e32 v22, s9, v14
	v_ashrrev_i32_e32 v23, 31, v22
	s_waitcnt lgkmcnt(7)
	v_cvt_pk_bf16_f32 v18, v76, v77
	ds_read2_b32 v[76:77], v17 offset0:24 offset1:57
	v_lshlrev_b64 v[22:23], 11, v[22:23]
	s_waitcnt lgkmcnt(7)
	v_cvt_pk_bf16_f32 v19, v78, v79
	ds_read2_b32 v[78:79], v17 offset0:90 offset1:123
	v_lshl_add_u64 v[22:23], v[24:25], 0, v[22:23]
	s_waitcnt lgkmcnt(7)
	v_cvt_pk_bf16_f32 v20, v80, v81
	ds_read2_b32 v[80:81], v17 offset0:156 offset1:189
	s_waitcnt lgkmcnt(7)
	v_cvt_pk_bf16_f32 v21, v236, v237
	ds_read2_b32 v[236:237], v17 offset0:222 offset1:255
	global_store_dwordx4 v[22:23], v[18:21], off
	v_or_b32_e32 v22, s9, v15
	v_ashrrev_i32_e32 v23, 31, v22
	s_waitcnt lgkmcnt(7)
	v_cvt_pk_bf16_f32 v18, v66, v67
	v_lshlrev_b64 v[22:23], 11, v[22:23]
	s_waitcnt lgkmcnt(6)
	v_cvt_pk_bf16_f32 v19, v70, v71
	v_lshl_add_u64 v[22:23], v[24:25], 0, v[22:23]
	s_waitcnt lgkmcnt(5)
	v_cvt_pk_bf16_f32 v20, v72, v73
	s_waitcnt lgkmcnt(4)
	v_cvt_pk_bf16_f32 v21, v74, v75
	global_store_dwordx4 v[22:23], v[18:21], off
	v_or_b32_e32 v22, s9, v16
	v_ashrrev_i32_e32 v23, 31, v22
	s_waitcnt lgkmcnt(3)
	v_cvt_pk_bf16_f32 v18, v76, v77
	v_lshlrev_b64 v[22:23], 11, v[22:23]
	s_waitcnt lgkmcnt(2)
	v_cvt_pk_bf16_f32 v19, v78, v79
	v_lshl_add_u64 v[22:23], v[24:25], 0, v[22:23]
	s_waitcnt lgkmcnt(1)
	v_cvt_pk_bf16_f32 v20, v80, v81
	s_waitcnt lgkmcnt(0)
	v_cvt_pk_bf16_f32 v21, v236, v237
	global_store_dwordx4 v[22:23], v[18:21], off
	s_waitcnt lgkmcnt(0)
	s_add_i32 s33, s33, s6
	s_cmpk_gt_i32 s33, 0x7ff
	s_cbranch_scc0 .LBB0_136

; template <bool MAP> __device__ __forceinline__ void p0_transpose_item(const float* W, int K, int NS, bf16* WT, LAS float* scr, int item, int nkb, int lane) {
;     ...
; #pragma unroll 8
;     for (int i = 0; i < 32; ++i) { const int kk = 2 * i + (lane >> 5); scr[kk * 33 + (lane & 31)] = W[(size_t)(k0 + kk) * NS + sc]; }
.LBB0_427:
	s_lshl_b32 s64, s42, 1
	s_lshl_b32 s65, s43, 1
	v_or_b32_e32 v200, s65, v6
	s_add_i32 s66, s64, 4
	s_add_i32 s67, s65, 4
	v_mov_b32_e32 v11, v201
	s_add_i32 s69, s65, 8
	v_lshlrev_b64 v[24:25], 12, v[200:201]
	v_or_b32_e32 v10, s66, v1
	v_or_b32_e32 v200, s67, v6
	v_mov_b32_e32 v9, v201
	v_or_b32_e32 v8, s64, v1
	s_add_i32 s71, s65, 12
	v_lshlrev_b64 v[10:11], 12, v[10:11]
	v_lshlrev_b64 v[26:27], 12, v[200:201]
	v_or_b32_e32 v200, s69, v6
	s_add_i32 s68, s64, 8
	s_add_i32 s70, s64, 12
	s_add_i32 s73, s65, 16
	v_lshlrev_b64 v[8:9], 12, v[8:9]
	v_lshl_add_u64 v[24:25], v[2:3], 0, v[24:25]
	v_lshl_add_u64 v[10:11], v[2:3], 0, v[10:11]
	v_lshlrev_b64 v[28:29], 12, v[200:201]
	v_or_b32_e32 v200, s71, v6
	v_mov_b32_e32 v13, v201
	v_mov_b32_e32 v15, v201
	s_add_i32 s75, s65, 20
	v_or_b32_e32 v12, s68, v1
	v_or_b32_e32 v14, s70, v1
	v_lshl_add_u64 v[8:9], v[2:3], 0, v[8:9]
	v_lshl_add_u64 v[26:27], v[2:3], 0, v[26:27]
	global_load_dword v5, v[24:25], off
	global_load_dword v7, v[8:9], off
	global_load_dword v40, v[26:27], off
	global_load_dword v41, v[10:11], off
	v_lshlrev_b64 v[10:11], 12, v[200:201]
	v_or_b32_e32 v200, s73, v6
	s_add_i32 s72, s64, 16
	s_add_i32 s74, s64, 20
	s_add_i32 s77, s65, 24
	v_lshlrev_b64 v[12:13], 12, v[12:13]
	v_lshlrev_b64 v[14:15], 12, v[14:15]
	v_lshl_add_u64 v[8:9], v[2:3], 0, v[28:29]
	v_lshl_add_u64 v[10:11], v[2:3], 0, v[10:11]
	v_lshlrev_b64 v[24:25], 12, v[200:201]
	v_or_b32_e32 v200, s75, v6
	v_mov_b32_e32 v17, v201
	v_mov_b32_e32 v19, v201
	s_add_i32 s76, s64, 24
	s_add_i32 s78, s64, 28
	s_add_i32 s79, s65, 28
	v_or_b32_e32 v16, s72, v1
	v_or_b32_e32 v18, s74, v1
	v_lshl_add_u64 v[12:13], v[2:3], 0, v[12:13]
	v_lshl_add_u64 v[14:15], v[2:3], 0, v[14:15]
	global_load_dword v42, v[8:9], off
	global_load_dword v43, v[12:13], off
	global_load_dword v44, v[10:11], off
	global_load_dword v45, v[14:15], off
	v_lshlrev_b64 v[10:11], 12, v[200:201]
	v_or_b32_e32 v200, s77, v6
	v_mov_b32_e32 v21, v201
	v_mov_b32_e32 v23, v201
	v_or_b32_e32 v20, s76, v1
	v_or_b32_e32 v22, s78, v1
	v_lshlrev_b64 v[16:17], 12, v[16:17]
	v_lshlrev_b64 v[18:19], 12, v[18:19]
	v_lshl_add_u64 v[8:9], v[2:3], 0, v[24:25]
	v_lshl_add_u64 v[10:11], v[2:3], 0, v[10:11]
	v_lshlrev_b64 v[12:13], 12, v[200:201]
	v_or_b32_e32 v200, s79, v6
	v_lshlrev_b64 v[20:21], 12, v[20:21]
	v_lshlrev_b64 v[22:23], 12, v[22:23]
	v_lshl_add_u64 v[16:17], v[2:3], 0, v[16:17]
	v_lshl_add_u64 v[18:19], v[2:3], 0, v[18:19]
	global_load_dword v46, v[8:9], off
	global_load_dword v47, v[16:17], off
	global_load_dword v48, v[10:11], off
	global_load_dword v49, v[18:19], off
	v_lshl_add_u64 v[8:9], v[2:3], 0, v[12:13]
	v_lshlrev_b64 v[10:11], 12, v[200:201]
	v_lshl_add_u64 v[20:21], v[2:3], 0, v[20:21]
	v_lshl_add_u64 v[22:23], v[2:3], 0, v[22:23]
	v_lshl_add_u64 v[10:11], v[2:3], 0, v[10:11]
	global_load_dword v50, v[8:9], off
	global_load_dword v51, v[20:21], off
	global_load_dword v52, v[10:11], off
	global_load_dword v53, v[22:23], off
	v_or_b32_e32 v10, s64, v199
	v_or_b32_e32 v8, s65, v198
	s_add_i32 s43, s43, 16
	s_add_i32 s42, s42, 16
	s_add_i32 s63, s63, -16
	v_or_b32_e32 v18, s68, v199
	v_or_b32_e32 v16, s69, v198
	v_or_b32_e32 v22, s70, v199
	v_or_b32_e32 v20, s71, v198
	v_or_b32_e32 v26, s72, v199
	v_or_b32_e32 v24, s73, v198
	v_or_b32_e32 v30, s74, v199
	v_or_b32_e32 v28, s75, v198
	v_or_b32_e32 v34, s76, v199
	v_or_b32_e32 v32, s77, v198
	v_or_b32_e32 v38, s78, v199
	v_or_b32_e32 v36, s79, v198
	s_cmp_lg_u32 s63, 0
	v_mad_u64_u32 v[8:9], s[64:65], v8, s46, v[4:5]
	v_mad_u64_u32 v[10:11], s[64:65], v10, s46, v[4:5]
	v_or_b32_e32 v9, s66, v199
	v_or_b32_e32 v11, s67, v198
	v_mad_u64_u32 v[12:13], s[64:65], v11, s46, v[4:5]
	v_mad_u64_u32 v[14:15], s[64:65], v9, s46, v[4:5]
	v_mad_u64_u32 v[16:17], s[64:65], v16, s46, v[4:5]
	v_mad_u64_u32 v[18:19], s[64:65], v18, s46, v[4:5]
	v_mad_u64_u32 v[20:21], s[64:65], v20, s46, v[4:5]
	v_mad_u64_u32 v[22:23], s[64:65], v22, s46, v[4:5]
	v_mad_u64_u32 v[24:25], s[64:65], v24, s46, v[4:5]
	v_mad_u64_u32 v[26:27], s[64:65], v26, s46, v[4:5]
	v_mad_u64_u32 v[28:29], s[64:65], v28, s46, v[4:5]
	v_mad_u64_u32 v[30:31], s[64:65], v30, s46, v[4:5]
	v_mad_u64_u32 v[32:33], s[64:65], v32, s46, v[4:5]
	v_mad_u64_u32 v[34:35], s[64:65], v34, s46, v[4:5]
	v_mad_u64_u32 v[36:37], s[64:65], v36, s46, v[4:5]
	v_mad_u64_u32 v[38:39], s[64:65], v38, s46, v[4:5]
	s_lshl_b32 s64, s42, 1
	s_lshl_b32 s65, s43, 1
	v_or_b32_e32 v200, s65, v6
	s_add_i32 s66, s64, 4
	s_add_i32 s67, s65, 4
	v_mov_b32_e32 v67, v201
	s_add_i32 s69, s65, 8
	v_lshlrev_b64 v[80:81], 12, v[200:201]
	v_or_b32_e32 v66, s66, v1
	v_or_b32_e32 v200, s67, v6
	v_mov_b32_e32 v65, v201
	v_or_b32_e32 v64, s64, v1
	s_add_i32 s71, s65, 12
	v_lshlrev_b64 v[66:67], 12, v[66:67]
	v_lshlrev_b64 v[82:83], 12, v[200:201]
	v_or_b32_e32 v200, s69, v6
	s_add_i32 s68, s64, 8
	s_add_i32 s70, s64, 12
	s_add_i32 s73, s65, 16
	v_lshlrev_b64 v[64:65], 12, v[64:65]
	v_lshl_add_u64 v[80:81], v[2:3], 0, v[80:81]
	v_lshl_add_u64 v[66:67], v[2:3], 0, v[66:67]
	v_lshlrev_b64 v[84:85], 12, v[200:201]
	v_or_b32_e32 v200, s71, v6
	v_mov_b32_e32 v69, v201
	v_mov_b32_e32 v71, v201
	s_add_i32 s75, s65, 20
	v_or_b32_e32 v68, s68, v1
	v_or_b32_e32 v70, s70, v1
	v_lshl_add_u64 v[64:65], v[2:3], 0, v[64:65]
	v_lshl_add_u64 v[82:83], v[2:3], 0, v[82:83]
	global_load_dword v61, v[80:81], off
	global_load_dword v63, v[64:65], off
	global_load_dword v96, v[82:83], off
	global_load_dword v97, v[66:67], off
	v_lshlrev_b64 v[66:67], 12, v[200:201]
	v_or_b32_e32 v200, s73, v6
	s_add_i32 s72, s64, 16
	s_add_i32 s74, s64, 20
	s_add_i32 s77, s65, 24
	v_lshlrev_b64 v[68:69], 12, v[68:69]
; template <bool MAP> __device__ __forceinline__ void p0_transpose_item(const float* W, int K, int NS, bf16* WT, LAS float* scr, int item, int nkb, int lane) {
;     ...
;     for (int i = 0; i < 32; ++i) { const int kk = 2 * i + (lane >> 5); scr[kk * 33 + (lane & 31)] = W[(size_t)(k0 + kk) * NS + sc]; }
	v_lshlrev_b64 v[70:71], 12, v[70:71]
	v_lshl_add_u64 v[64:65], v[2:3], 0, v[84:85]
	v_lshl_add_u64 v[66:67], v[2:3], 0, v[66:67]
	v_lshlrev_b64 v[80:81], 12, v[200:201]
	v_or_b32_e32 v200, s75, v6
	v_mov_b32_e32 v73, v201
	v_mov_b32_e32 v75, v201
	s_add_i32 s76, s64, 24
	s_add_i32 s78, s64, 28
	s_add_i32 s79, s65, 28
	v_or_b32_e32 v72, s72, v1
	v_or_b32_e32 v74, s74, v1
	v_lshl_add_u64 v[68:69], v[2:3], 0, v[68:69]
	v_lshl_add_u64 v[70:71], v[2:3], 0, v[70:71]
	global_load_dword v98, v[64:65], off
	global_load_dword v99, v[68:69], off
	global_load_dword v100, v[66:67], off
	global_load_dword v101, v[70:71], off
	v_lshlrev_b64 v[66:67], 12, v[200:201]
	v_or_b32_e32 v200, s77, v6
	v_mov_b32_e32 v77, v201
	v_mov_b32_e32 v79, v201
	v_or_b32_e32 v76, s76, v1
	v_or_b32_e32 v78, s78, v1
	v_lshlrev_b64 v[72:73], 12, v[72:73]
	v_lshlrev_b64 v[74:75], 12, v[74:75]
	v_lshl_add_u64 v[64:65], v[2:3], 0, v[80:81]
	v_lshl_add_u64 v[66:67], v[2:3], 0, v[66:67]
	v_lshlrev_b64 v[68:69], 12, v[200:201]
	v_or_b32_e32 v200, s79, v6
	v_lshlrev_b64 v[76:77], 12, v[76:77]
	v_lshlrev_b64 v[78:79], 12, v[78:79]
	v_lshl_add_u64 v[72:73], v[2:3], 0, v[72:73]
	v_lshl_add_u64 v[74:75], v[2:3], 0, v[74:75]
	global_load_dword v102, v[64:65], off
	global_load_dword v103, v[72:73], off
	global_load_dword v104, v[66:67], off
	global_load_dword v105, v[74:75], off
	v_lshl_add_u64 v[64:65], v[2:3], 0, v[68:69]
	v_lshlrev_b64 v[66:67], 12, v[200:201]
	v_lshl_add_u64 v[76:77], v[2:3], 0, v[76:77]
	v_lshl_add_u64 v[78:79], v[2:3], 0, v[78:79]
	v_lshl_add_u64 v[66:67], v[2:3], 0, v[66:67]
	global_load_dword v106, v[64:65], off
	global_load_dword v107, v[76:77], off
	global_load_dword v108, v[66:67], off
	global_load_dword v109, v[78:79], off
	s_waitcnt vmcnt(31)
	ds_write_b32 v8, v5
	s_waitcnt vmcnt(30)
	ds_write_b32 v10, v7
	s_waitcnt vmcnt(29)
	ds_write_b32 v12, v40
	s_waitcnt vmcnt(28)
	ds_write_b32 v14, v41
	s_waitcnt vmcnt(27)
	ds_write_b32 v16, v42
	s_waitcnt vmcnt(26)
	ds_write_b32 v18, v43
	s_waitcnt vmcnt(25)
	ds_write_b32 v20, v44
	s_waitcnt vmcnt(24)
	ds_write_b32 v22, v45
	s_waitcnt vmcnt(23)
	ds_write_b32 v24, v46
	s_waitcnt vmcnt(22)
	ds_write_b32 v26, v47
	s_waitcnt vmcnt(21)
	ds_write_b32 v28, v48
	s_waitcnt vmcnt(20)
	ds_write_b32 v30, v49
	s_waitcnt vmcnt(19)
	ds_write_b32 v32, v50
	s_waitcnt vmcnt(18)
	ds_write_b32 v34, v51
	s_waitcnt vmcnt(17)
	ds_write_b32 v36, v52
	s_waitcnt vmcnt(16)
	ds_write_b32 v38, v53
	v_or_b32_e32 v10, s64, v199
	v_or_b32_e32 v8, s65, v198
	s_add_i32 s43, s43, 16
	s_add_i32 s42, s42, 16
	s_add_i32 s63, s63, -16
	v_or_b32_e32 v18, s68, v199
	v_or_b32_e32 v16, s69, v198
	v_or_b32_e32 v22, s70, v199
	v_or_b32_e32 v20, s71, v198
	v_or_b32_e32 v26, s72, v199
	v_or_b32_e32 v24, s73, v198
	v_or_b32_e32 v30, s74, v199
	v_or_b32_e32 v28, s75, v198
	v_or_b32_e32 v34, s76, v199
	v_or_b32_e32 v32, s77, v198
	v_or_b32_e32 v38, s78, v199
	v_or_b32_e32 v36, s79, v198
	s_cmp_lg_u32 s63, 0
	v_mad_u64_u32 v[8:9], s[64:65], v8, s46, v[4:5]
	v_mad_u64_u32 v[10:11], s[64:65], v10, s46, v[4:5]
	v_or_b32_e32 v9, s66, v199
	v_or_b32_e32 v11, s67, v198
	v_mad_u64_u32 v[12:13], s[64:65], v11, s46, v[4:5]
	v_mad_u64_u32 v[14:15], s[64:65], v9, s46, v[4:5]
	v_mad_u64_u32 v[16:17], s[64:65], v16, s46, v[4:5]
	v_mad_u64_u32 v[18:19], s[64:65], v18, s46, v[4:5]
	v_mad_u64_u32 v[20:21], s[64:65], v20, s46, v[4:5]
	v_mad_u64_u32 v[22:23], s[64:65], v22, s46, v[4:5]
	v_mad_u64_u32 v[24:25], s[64:65], v24, s46, v[4:5]
	v_mad_u64_u32 v[26:27], s[64:65], v26, s46, v[4:5]
	v_mad_u64_u32 v[28:29], s[64:65], v28, s46, v[4:5]
	v_mad_u64_u32 v[30:31], s[64:65], v30, s46, v[4:5]
	v_mad_u64_u32 v[32:33], s[64:65], v32, s46, v[4:5]
	v_mad_u64_u32 v[34:35], s[64:65], v34, s46, v[4:5]
	v_mad_u64_u32 v[36:37], s[64:65], v36, s46, v[4:5]
	v_mad_u64_u32 v[38:39], s[64:65], v38, s46, v[4:5]
	s_waitcnt vmcnt(15)
; #define GAS __attribute__((address_space(1)))
; #define LAS __attribute__((address_space(3)))
; #define LDS_WAIT() asm volatile("s_waitcnt lgkmcnt(0)" ::: "memory")
; __device__ __forceinline__ unsigned pk2(float lo, float hi) { return pg8::cvt_pk_bf16(lo, hi); }
; template <bool MAP> __device__ __forceinline__ void p0_transpose_item(const float* W, int K, int NS, bf16* WT, LAS float* scr, int item, int nkb, int lane) {
;     ...
;     for (int i = 0; i < 32; ++i) { const int kk = 2 * i + (lane >> 5); scr[kk * 33 + (lane & 31)] = W[(size_t)(k0 + kk) * NS + sc]; }
;     LDS_WAIT(); asm volatile("" ::: "memory");
;     const int c = lane & 7;
; #pragma unroll
;     for (int j = 0; j < 4; ++j) { const int n = (lane >> 3) + 8 * j; const LAS float* s = scr + (8 * c) * 33 + n;
;         v4u o; o.x = pk2(s[0 * 33], s[1 * 33]); o.y = pk2(s[2 * 33], s[3 * 33]); o.z = pk2(s[4 * 33], s[5 * 33]); o.w = pk2(s[6 * 33], s[7 * 33]);
;         *(GAS v4u*)(WT + (size_t)(p0 + n) * K + k0 + 8 * c) = o; }
;     LDS_WAIT(); asm volatile("" ::: "memory");
	ds_write_b32 v8, v61
	s_waitcnt vmcnt(14)
	ds_write_b32 v10, v63
	s_waitcnt vmcnt(13)
	ds_write_b32 v12, v96
	s_waitcnt vmcnt(12)
	ds_write_b32 v14, v97
	s_waitcnt vmcnt(11)
	ds_write_b32 v16, v98
	s_waitcnt vmcnt(10)
	ds_write_b32 v18, v99
	s_waitcnt vmcnt(9)
	ds_write_b32 v20, v100
	s_waitcnt vmcnt(8)
	ds_write_b32 v22, v101
	s_waitcnt vmcnt(7)
	ds_write_b32 v24, v102
	s_waitcnt vmcnt(6)
	ds_write_b32 v26, v103
	s_waitcnt vmcnt(5)
	ds_write_b32 v28, v104
	s_waitcnt vmcnt(4)
	ds_write_b32 v30, v105
	s_waitcnt vmcnt(3)
	ds_write_b32 v32, v106
	s_waitcnt vmcnt(2)
	ds_write_b32 v34, v107
	s_waitcnt vmcnt(1)
	ds_write_b32 v36, v108
	s_waitcnt vmcnt(0)
	ds_write_b32 v38, v109
	s_lshl_b32 s41, s41, 1
	s_waitcnt lgkmcnt(0)
	v_lshlrev_b32_e32 v1, 2, v233
	v_mul_u32_u24_e32 v2, 0x84, v204
	s_add_u32 s42, s6, s41
	v_add3_u32 v1, s12, v2, v1
	v_lshlrev_b32_e32 v200, 1, v204
	s_addc_u32 s43, s7, 0
	ds_read2_b32 v[40:41], v1 offset1:33
	ds_read2_b32 v[42:43], v1 offset0:66 offset1:99
	ds_read2_b32 v[44:45], v1 offset0:132 offset1:165
	ds_read2_b32 v[46:47], v1 offset0:198 offset1:231
	ds_read2_b32 v[48:49], v1 offset0:8 offset1:41
	ds_read2_b32 v[50:51], v1 offset0:74 offset1:107
	ds_read2_b32 v[52:53], v1 offset0:140 offset1:173
	ds_read2_b32 v[96:97], v1 offset0:206 offset1:239
	v_lshl_add_u64 v[8:9], s[42:43], 0, v[200:201]
	v_or_b32_e32 v200, s40, v233
	s_waitcnt lgkmcnt(7)
	v_cvt_pk_bf16_f32 v2, v40, v41
	ds_read2_b32 v[40:41], v1 offset0:16 offset1:49
	v_lshl_add_u64 v[8:9], v[8:9], 0, s[34:35]
	v_lshlrev_b64 v[10:11], 11, v[200:201]
	s_waitcnt lgkmcnt(7)
	v_cvt_pk_bf16_f32 v3, v42, v43
	ds_read2_b32 v[42:43], v1 offset0:82 offset1:115
	v_lshl_add_u64 v[10:11], v[8:9], 0, v[10:11]
	s_waitcnt lgkmcnt(7)
	v_cvt_pk_bf16_f32 v4, v44, v45
	ds_read2_b32 v[44:45], v1 offset0:148 offset1:181
	s_waitcnt lgkmcnt(7)
	v_cvt_pk_bf16_f32 v5, v46, v47
	ds_read2_b32 v[46:47], v1 offset0:214 offset1:247
	global_store_dwordx4 v[10:11], v[2:5], off
	v_or_b32_e32 v10, 8, v233
	v_or_b32_e32 v200, s40, v10
	s_waitcnt lgkmcnt(7)
	v_cvt_pk_bf16_f32 v2, v48, v49
	ds_read2_b32 v[48:49], v1 offset0:24 offset1:57
	v_lshlrev_b64 v[10:11], 11, v[200:201]
	s_waitcnt lgkmcnt(7)
	v_cvt_pk_bf16_f32 v3, v50, v51
	ds_read2_b32 v[50:51], v1 offset0:90 offset1:123
	v_lshl_add_u64 v[10:11], v[8:9], 0, v[10:11]
	s_waitcnt lgkmcnt(7)
	v_cvt_pk_bf16_f32 v4, v52, v53
	ds_read2_b32 v[52:53], v1 offset0:156 offset1:189
	s_waitcnt lgkmcnt(7)
	v_cvt_pk_bf16_f32 v5, v96, v97
	ds_read2_b32 v[96:97], v1 offset0:222 offset1:255
	global_store_dwordx4 v[10:11], v[2:5], off
	v_or_b32_e32 v10, 16, v233
	s_waitcnt lgkmcnt(7)
	v_cvt_pk_bf16_f32 v2, v40, v41
	v_or_b32_e32 v200, s40, v10
	s_waitcnt lgkmcnt(6)
	v_cvt_pk_bf16_f32 v3, v42, v43
	v_lshlrev_b64 v[10:11], 11, v[200:201]
	s_waitcnt lgkmcnt(5)
	v_cvt_pk_bf16_f32 v4, v44, v45
	s_waitcnt lgkmcnt(4)
	v_cvt_pk_bf16_f32 v5, v46, v47
	v_lshl_add_u64 v[10:11], v[8:9], 0, v[10:11]
	global_store_dwordx4 v[10:11], v[2:5], off
	s_mov_b64 s[42:43], 0
	s_waitcnt lgkmcnt(3)
	v_cvt_pk_bf16_f32 v2, v48, v49
	s_waitcnt lgkmcnt(2)
	v_cvt_pk_bf16_f32 v3, v50, v51
	s_waitcnt lgkmcnt(1)
	v_cvt_pk_bf16_f32 v4, v52, v53
	v_or_b32_e32 v1, 24, v233
	v_or_b32_e32 v200, s40, v1
	v_lshlrev_b64 v[10:11], 11, v[200:201]
	s_waitcnt lgkmcnt(0)
	v_cvt_pk_bf16_f32 v5, v96, v97
	v_lshl_add_u64 v[6:7], v[8:9], 0, v[10:11]
	global_store_dwordx4 v[6:7], v[2:5], off
	s_waitcnt lgkmcnt(0)

; template <bool MAP> __device__ __forceinline__ void p0_transpose_item(const float* W, int K, int NS, bf16* WT, LAS float* scr, int item, int nkb, int lane) {
;     ...
; #pragma unroll 8
;     for (int i = 0; i < 32; ++i) { const int kk = 2 * i + (lane >> 5); scr[kk * 33 + (lane & 31)] = W[(size_t)(k0 + kk) * NS + sc]; }
.LBB0_431:
	s_lshl_b32 s43, s10, 1
	s_lshl_b32 s63, s11, 1
	v_or_b32_e32 v200, s63, v6
	s_add_i32 s66, s43, 4
	s_add_i32 s67, s63, 4
	v_mov_b32_e32 v11, v201
	s_add_i32 s69, s63, 8
	v_lshlrev_b64 v[24:25], 12, v[200:201]
	v_or_b32_e32 v10, s66, v1
	v_or_b32_e32 v200, s67, v6
	v_mov_b32_e32 v9, v201
	v_or_b32_e32 v8, s43, v1
	s_add_i32 s71, s63, 12
	v_lshlrev_b64 v[10:11], 12, v[10:11]
	v_lshlrev_b64 v[26:27], 12, v[200:201]
	v_or_b32_e32 v200, s69, v6
	s_add_i32 s68, s43, 8
	s_add_i32 s70, s43, 12
	s_add_i32 s73, s63, 16
	v_lshlrev_b64 v[8:9], 12, v[8:9]
	v_lshl_add_u64 v[24:25], v[2:3], 0, v[24:25]
	v_lshl_add_u64 v[10:11], v[2:3], 0, v[10:11]
	v_lshlrev_b64 v[28:29], 12, v[200:201]
	v_or_b32_e32 v200, s71, v6
	v_mov_b32_e32 v13, v201
	v_mov_b32_e32 v15, v201
	s_add_i32 s75, s63, 20
	v_or_b32_e32 v12, s68, v1
	v_or_b32_e32 v14, s70, v1
	v_lshl_add_u64 v[8:9], v[2:3], 0, v[8:9]
	v_lshl_add_u64 v[26:27], v[2:3], 0, v[26:27]
	global_load_dword v5, v[24:25], off
	global_load_dword v7, v[8:9], off
	global_load_dword v40, v[26:27], off
	global_load_dword v41, v[10:11], off
	v_lshlrev_b64 v[10:11], 12, v[200:201]
	v_or_b32_e32 v200, s73, v6
	s_add_i32 s72, s43, 16
	s_add_i32 s74, s43, 20
	s_add_i32 s77, s63, 24
	v_lshlrev_b64 v[12:13], 12, v[12:13]
	v_lshlrev_b64 v[14:15], 12, v[14:15]
	v_lshl_add_u64 v[8:9], v[2:3], 0, v[28:29]
	v_lshl_add_u64 v[10:11], v[2:3], 0, v[10:11]
	v_lshlrev_b64 v[24:25], 12, v[200:201]
	v_or_b32_e32 v200, s75, v6
	v_mov_b32_e32 v17, v201
	v_mov_b32_e32 v19, v201
	s_add_i32 s76, s43, 24
	s_add_i32 s78, s43, 28
	s_add_i32 s79, s63, 28
	v_or_b32_e32 v16, s72, v1
	v_or_b32_e32 v18, s74, v1
	v_lshl_add_u64 v[12:13], v[2:3], 0, v[12:13]
	v_lshl_add_u64 v[14:15], v[2:3], 0, v[14:15]
	global_load_dword v42, v[8:9], off
	global_load_dword v43, v[12:13], off
	global_load_dword v44, v[10:11], off
	global_load_dword v45, v[14:15], off
	v_lshlrev_b64 v[10:11], 12, v[200:201]
	v_or_b32_e32 v200, s77, v6
	v_mov_b32_e32 v21, v201
	v_mov_b32_e32 v23, v201
	v_or_b32_e32 v20, s76, v1
	v_or_b32_e32 v22, s78, v1
	v_lshlrev_b64 v[16:17], 12, v[16:17]
	v_lshlrev_b64 v[18:19], 12, v[18:19]
	v_lshl_add_u64 v[8:9], v[2:3], 0, v[24:25]
	v_lshl_add_u64 v[10:11], v[2:3], 0, v[10:11]
	v_lshlrev_b64 v[12:13], 12, v[200:201]
	v_or_b32_e32 v200, s79, v6
	v_lshlrev_b64 v[20:21], 12, v[20:21]
	v_lshlrev_b64 v[22:23], 12, v[22:23]
	v_lshl_add_u64 v[16:17], v[2:3], 0, v[16:17]
	v_lshl_add_u64 v[18:19], v[2:3], 0, v[18:19]
	global_load_dword v46, v[8:9], off
	global_load_dword v47, v[16:17], off
	global_load_dword v48, v[10:11], off
	global_load_dword v49, v[18:19], off
	v_lshl_add_u64 v[8:9], v[2:3], 0, v[12:13]
	v_lshlrev_b64 v[10:11], 12, v[200:201]
	v_lshl_add_u64 v[20:21], v[2:3], 0, v[20:21]
	v_lshl_add_u64 v[22:23], v[2:3], 0, v[22:23]
	v_lshl_add_u64 v[10:11], v[2:3], 0, v[10:11]
	global_load_dword v50, v[8:9], off
	global_load_dword v51, v[20:21], off
	global_load_dword v52, v[10:11], off
	global_load_dword v53, v[22:23], off
	v_or_b32_e32 v10, s43, v199
	v_or_b32_e32 v8, s63, v198
	s_add_i32 s11, s11, 16
	s_add_i32 s10, s10, 16
	s_add_i32 s42, s42, -16
	v_or_b32_e32 v18, s68, v199
	v_or_b32_e32 v16, s69, v198
	v_or_b32_e32 v22, s70, v199
	v_or_b32_e32 v20, s71, v198
	v_or_b32_e32 v26, s72, v199
	v_or_b32_e32 v24, s73, v198
	v_or_b32_e32 v30, s74, v199
	v_or_b32_e32 v28, s75, v198
	v_or_b32_e32 v34, s76, v199
	v_or_b32_e32 v32, s77, v198
	v_or_b32_e32 v38, s78, v199
	v_or_b32_e32 v36, s79, v198
	s_cmp_lg_u32 s42, 0
	v_mad_u64_u32 v[8:9], s[64:65], v8, s46, v[4:5]
	v_mad_u64_u32 v[10:11], s[64:65], v10, s46, v[4:5]
	v_or_b32_e32 v9, s66, v199
	v_or_b32_e32 v11, s67, v198
	v_mad_u64_u32 v[12:13], s[64:65], v11, s46, v[4:5]
	v_mad_u64_u32 v[14:15], s[64:65], v9, s46, v[4:5]
	v_mad_u64_u32 v[16:17], s[64:65], v16, s46, v[4:5]
	v_mad_u64_u32 v[18:19], s[64:65], v18, s46, v[4:5]
	v_mad_u64_u32 v[20:21], s[64:65], v20, s46, v[4:5]
	v_mad_u64_u32 v[22:23], s[64:65], v22, s46, v[4:5]
	v_mad_u64_u32 v[24:25], s[64:65], v24, s46, v[4:5]
	v_mad_u64_u32 v[26:27], s[64:65], v26, s46, v[4:5]
	v_mad_u64_u32 v[28:29], s[64:65], v28, s46, v[4:5]
	v_mad_u64_u32 v[30:31], s[64:65], v30, s46, v[4:5]
	v_mad_u64_u32 v[32:33], s[64:65], v32, s46, v[4:5]
	v_mad_u64_u32 v[34:35], s[64:65], v34, s46, v[4:5]
	v_mad_u64_u32 v[36:37], s[64:65], v36, s46, v[4:5]
	v_mad_u64_u32 v[38:39], s[64:65], v38, s46, v[4:5]
	s_lshl_b32 s43, s10, 1
	s_lshl_b32 s63, s11, 1
	v_or_b32_e32 v200, s63, v6
	s_add_i32 s66, s43, 4
	s_add_i32 s67, s63, 4
	v_mov_b32_e32 v67, v201
	s_add_i32 s69, s63, 8
	v_lshlrev_b64 v[80:81], 12, v[200:201]
	v_or_b32_e32 v66, s66, v1
	v_or_b32_e32 v200, s67, v6
	v_mov_b32_e32 v65, v201
	v_or_b32_e32 v64, s43, v1
	s_add_i32 s71, s63, 12
	v_lshlrev_b64 v[66:67], 12, v[66:67]
	v_lshlrev_b64 v[82:83], 12, v[200:201]
	v_or_b32_e32 v200, s69, v6
	s_add_i32 s68, s43, 8
	s_add_i32 s70, s43, 12
	s_add_i32 s73, s63, 16
	v_lshlrev_b64 v[64:65], 12, v[64:65]
	v_lshl_add_u64 v[80:81], v[2:3], 0, v[80:81]
	v_lshl_add_u64 v[66:67], v[2:3], 0, v[66:67]
	v_lshlrev_b64 v[84:85], 12, v[200:201]
	v_or_b32_e32 v200, s71, v6
	v_mov_b32_e32 v69, v201
	v_mov_b32_e32 v71, v201
	s_add_i32 s75, s63, 20
	v_or_b32_e32 v68, s68, v1
	v_or_b32_e32 v70, s70, v1
	v_lshl_add_u64 v[64:65], v[2:3], 0, v[64:65]
	v_lshl_add_u64 v[82:83], v[2:3], 0, v[82:83]
	global_load_dword v61, v[80:81], off
	global_load_dword v63, v[64:65], off
	global_load_dword v96, v[82:83], off
	global_load_dword v97, v[66:67], off
	v_lshlrev_b64 v[66:67], 12, v[200:201]
	v_or_b32_e32 v200, s73, v6
	s_add_i32 s72, s43, 16
	s_add_i32 s74, s43, 20
	s_add_i32 s77, s63, 24
	v_lshlrev_b64 v[68:69], 12, v[68:69]
; template <bool MAP> __device__ __forceinline__ void p0_transpose_item(const float* W, int K, int NS, bf16* WT, LAS float* scr, int item, int nkb, int lane) {
;     ...
;     for (int i = 0; i < 32; ++i) { const int kk = 2 * i + (lane >> 5); scr[kk * 33 + (lane & 31)] = W[(size_t)(k0 + kk) * NS + sc]; }
	v_lshlrev_b64 v[70:71], 12, v[70:71]
	v_lshl_add_u64 v[64:65], v[2:3], 0, v[84:85]
	v_lshl_add_u64 v[66:67], v[2:3], 0, v[66:67]
	v_lshlrev_b64 v[80:81], 12, v[200:201]
	v_or_b32_e32 v200, s75, v6
	v_mov_b32_e32 v73, v201
	v_mov_b32_e32 v75, v201
	s_add_i32 s76, s43, 24
	s_add_i32 s78, s43, 28
	s_add_i32 s79, s63, 28
	v_or_b32_e32 v72, s72, v1
	v_or_b32_e32 v74, s74, v1
	v_lshl_add_u64 v[68:69], v[2:3], 0, v[68:69]
	v_lshl_add_u64 v[70:71], v[2:3], 0, v[70:71]
	global_load_dword v98, v[64:65], off
	global_load_dword v99, v[68:69], off
	global_load_dword v100, v[66:67], off
	global_load_dword v101, v[70:71], off
	v_lshlrev_b64 v[66:67], 12, v[200:201]
	v_or_b32_e32 v200, s77, v6
	v_mov_b32_e32 v77, v201
	v_mov_b32_e32 v79, v201
	v_or_b32_e32 v76, s76, v1
	v_or_b32_e32 v78, s78, v1
	v_lshlrev_b64 v[72:73], 12, v[72:73]
	v_lshlrev_b64 v[74:75], 12, v[74:75]
	v_lshl_add_u64 v[64:65], v[2:3], 0, v[80:81]
	v_lshl_add_u64 v[66:67], v[2:3], 0, v[66:67]
	v_lshlrev_b64 v[68:69], 12, v[200:201]
	v_or_b32_e32 v200, s79, v6
	v_lshlrev_b64 v[76:77], 12, v[76:77]
	v_lshlrev_b64 v[78:79], 12, v[78:79]
	v_lshl_add_u64 v[72:73], v[2:3], 0, v[72:73]
	v_lshl_add_u64 v[74:75], v[2:3], 0, v[74:75]
	global_load_dword v102, v[64:65], off
	global_load_dword v103, v[72:73], off
	global_load_dword v104, v[66:67], off
	global_load_dword v105, v[74:75], off
	v_lshl_add_u64 v[64:65], v[2:3], 0, v[68:69]
	v_lshlrev_b64 v[66:67], 12, v[200:201]
	v_lshl_add_u64 v[76:77], v[2:3], 0, v[76:77]
	v_lshl_add_u64 v[78:79], v[2:3], 0, v[78:79]
	v_lshl_add_u64 v[66:67], v[2:3], 0, v[66:67]
	global_load_dword v106, v[64:65], off
	global_load_dword v107, v[76:77], off
	global_load_dword v108, v[66:67], off
	global_load_dword v109, v[78:79], off
	s_waitcnt vmcnt(31)
	ds_write_b32 v8, v5
	s_waitcnt vmcnt(30)
	ds_write_b32 v10, v7
	s_waitcnt vmcnt(29)
	ds_write_b32 v12, v40
	s_waitcnt vmcnt(28)
	ds_write_b32 v14, v41
	s_waitcnt vmcnt(27)
	ds_write_b32 v16, v42
	s_waitcnt vmcnt(26)
	ds_write_b32 v18, v43
	s_waitcnt vmcnt(25)
	ds_write_b32 v20, v44
	s_waitcnt vmcnt(24)
	ds_write_b32 v22, v45
	s_waitcnt vmcnt(23)
	ds_write_b32 v24, v46
	s_waitcnt vmcnt(22)
	ds_write_b32 v26, v47
	s_waitcnt vmcnt(21)
	ds_write_b32 v28, v48
	s_waitcnt vmcnt(20)
	ds_write_b32 v30, v49
	s_waitcnt vmcnt(19)
	ds_write_b32 v32, v50
	s_waitcnt vmcnt(18)
	ds_write_b32 v34, v51
	s_waitcnt vmcnt(17)
	ds_write_b32 v36, v52
	s_waitcnt vmcnt(16)
	ds_write_b32 v38, v53
	v_or_b32_e32 v10, s43, v199
	v_or_b32_e32 v8, s63, v198
	s_add_i32 s11, s11, 16
	s_add_i32 s10, s10, 16
	s_add_i32 s42, s42, -16
	v_or_b32_e32 v18, s68, v199
	v_or_b32_e32 v16, s69, v198
	v_or_b32_e32 v22, s70, v199
	v_or_b32_e32 v20, s71, v198
	v_or_b32_e32 v26, s72, v199
	v_or_b32_e32 v24, s73, v198
	v_or_b32_e32 v30, s74, v199
	v_or_b32_e32 v28, s75, v198
	v_or_b32_e32 v34, s76, v199
	v_or_b32_e32 v32, s77, v198
	v_or_b32_e32 v38, s78, v199
	v_or_b32_e32 v36, s79, v198
	s_cmp_lg_u32 s42, 0
	v_mad_u64_u32 v[8:9], s[64:65], v8, s46, v[4:5]
	v_mad_u64_u32 v[10:11], s[64:65], v10, s46, v[4:5]
	v_or_b32_e32 v9, s66, v199
	v_or_b32_e32 v11, s67, v198
	v_mad_u64_u32 v[12:13], s[64:65], v11, s46, v[4:5]
	v_mad_u64_u32 v[14:15], s[64:65], v9, s46, v[4:5]
	v_mad_u64_u32 v[16:17], s[64:65], v16, s46, v[4:5]
	v_mad_u64_u32 v[18:19], s[64:65], v18, s46, v[4:5]
	v_mad_u64_u32 v[20:21], s[64:65], v20, s46, v[4:5]
	v_mad_u64_u32 v[22:23], s[64:65], v22, s46, v[4:5]
	v_mad_u64_u32 v[24:25], s[64:65], v24, s46, v[4:5]
	v_mad_u64_u32 v[26:27], s[64:65], v26, s46, v[4:5]
	v_mad_u64_u32 v[28:29], s[64:65], v28, s46, v[4:5]
	v_mad_u64_u32 v[30:31], s[64:65], v30, s46, v[4:5]
	v_mad_u64_u32 v[32:33], s[64:65], v32, s46, v[4:5]
	v_mad_u64_u32 v[34:35], s[64:65], v34, s46, v[4:5]
	v_mad_u64_u32 v[36:37], s[64:65], v36, s46, v[4:5]
	v_mad_u64_u32 v[38:39], s[64:65], v38, s46, v[4:5]
	s_waitcnt vmcnt(15)
; #define GAS __attribute__((address_space(1)))
; #define LAS __attribute__((address_space(3)))
; #define LDS_WAIT() asm volatile("s_waitcnt lgkmcnt(0)" ::: "memory")
; __device__ __forceinline__ unsigned pk2(float lo, float hi) { return pg8::cvt_pk_bf16(lo, hi); }
; template <bool MAP> __device__ __forceinline__ void p0_transpose_item(const float* W, int K, int NS, bf16* WT, LAS float* scr, int item, int nkb, int lane) {
;     ...
;     for (int i = 0; i < 32; ++i) { const int kk = 2 * i + (lane >> 5); scr[kk * 33 + (lane & 31)] = W[(size_t)(k0 + kk) * NS + sc]; }
;     LDS_WAIT(); asm volatile("" ::: "memory");
;     const int c = lane & 7;
; #pragma unroll
;     for (int j = 0; j < 4; ++j) { const int n = (lane >> 3) + 8 * j; const LAS float* s = scr + (8 * c) * 33 + n;
;         v4u o; o.x = pk2(s[0 * 33], s[1 * 33]); o.y = pk2(s[2 * 33], s[3 * 33]); o.z = pk2(s[4 * 33], s[5 * 33]); o.w = pk2(s[6 * 33], s[7 * 33]);
;         *(GAS v4u*)(WT + (size_t)(p0 + n) * K + k0 + 8 * c) = o; }
;     LDS_WAIT(); asm volatile("" ::: "memory");
	ds_write_b32 v8, v61
	s_waitcnt vmcnt(14)
	ds_write_b32 v10, v63
	s_waitcnt vmcnt(13)
	ds_write_b32 v12, v96
	s_waitcnt vmcnt(12)
	ds_write_b32 v14, v97
	s_waitcnt vmcnt(11)
	ds_write_b32 v16, v98
	s_waitcnt vmcnt(10)
	ds_write_b32 v18, v99
	s_waitcnt vmcnt(9)
	ds_write_b32 v20, v100
	s_waitcnt vmcnt(8)
	ds_write_b32 v22, v101
	s_waitcnt vmcnt(7)
	ds_write_b32 v24, v102
	s_waitcnt vmcnt(6)
	ds_write_b32 v26, v103
	s_waitcnt vmcnt(5)
	ds_write_b32 v28, v104
	s_waitcnt vmcnt(4)
	ds_write_b32 v30, v105
	s_waitcnt vmcnt(3)
	ds_write_b32 v32, v106
	s_waitcnt vmcnt(2)
	ds_write_b32 v34, v107
	s_waitcnt vmcnt(1)
	ds_write_b32 v36, v108
	s_waitcnt vmcnt(0)
	ds_write_b32 v38, v109
	s_lshl_b32 s10, s41, 1
	s_waitcnt lgkmcnt(0)
	v_lshlrev_b32_e32 v1, 2, v233
	v_mul_u32_u24_e32 v2, 0x84, v204
	s_add_u32 s10, s6, s10
	v_add3_u32 v1, s12, v2, v1
	v_lshlrev_b32_e32 v200, 1, v204
	s_addc_u32 s11, s7, 0
	ds_read2_b32 v[40:41], v1 offset1:33
	ds_read2_b32 v[42:43], v1 offset0:66 offset1:99
	ds_read2_b32 v[44:45], v1 offset0:132 offset1:165
	ds_read2_b32 v[46:47], v1 offset0:198 offset1:231
	ds_read2_b32 v[48:49], v1 offset0:8 offset1:41
	ds_read2_b32 v[50:51], v1 offset0:74 offset1:107
	ds_read2_b32 v[52:53], v1 offset0:140 offset1:173
	ds_read2_b32 v[96:97], v1 offset0:206 offset1:239
	v_or_b32_e32 v10, s40, v233
	v_lshl_add_u64 v[8:9], s[10:11], 0, v[200:201]
	s_waitcnt lgkmcnt(7)
	v_cvt_pk_bf16_f32 v2, v40, v41
	ds_read2_b32 v[40:41], v1 offset0:16 offset1:49
	v_lshlrev_b32_e32 v200, 11, v10
	v_lshl_add_u64 v[8:9], v[8:9], 0, s[36:37]
	s_waitcnt lgkmcnt(7)
	v_cvt_pk_bf16_f32 v3, v42, v43
	ds_read2_b32 v[42:43], v1 offset0:82 offset1:115
	v_lshl_add_u64 v[10:11], v[8:9], 0, v[200:201]
	s_waitcnt lgkmcnt(7)
	v_cvt_pk_bf16_f32 v4, v44, v45
	ds_read2_b32 v[44:45], v1 offset0:148 offset1:181
	s_waitcnt lgkmcnt(7)
	v_cvt_pk_bf16_f32 v5, v46, v47
	ds_read2_b32 v[46:47], v1 offset0:214 offset1:247
	global_store_dwordx4 v[10:11], v[2:5], off
	v_or_b32_e32 v10, 8, v233
	v_or_b32_e32 v10, s40, v10
	s_waitcnt lgkmcnt(7)
	v_cvt_pk_bf16_f32 v2, v48, v49
	ds_read2_b32 v[48:49], v1 offset0:24 offset1:57
	v_lshlrev_b32_e32 v200, 11, v10
	s_waitcnt lgkmcnt(7)
	v_cvt_pk_bf16_f32 v3, v50, v51
	ds_read2_b32 v[50:51], v1 offset0:90 offset1:123
	v_lshl_add_u64 v[10:11], v[8:9], 0, v[200:201]
	s_waitcnt lgkmcnt(7)
	v_cvt_pk_bf16_f32 v4, v52, v53
	ds_read2_b32 v[52:53], v1 offset0:156 offset1:189
	s_waitcnt lgkmcnt(7)
	v_cvt_pk_bf16_f32 v5, v96, v97
	ds_read2_b32 v[96:97], v1 offset0:222 offset1:255
	global_store_dwordx4 v[10:11], v[2:5], off
	v_or_b32_e32 v10, 16, v233
	s_waitcnt lgkmcnt(7)
	v_cvt_pk_bf16_f32 v2, v40, v41
	v_or_b32_e32 v10, s40, v10
	s_waitcnt lgkmcnt(6)
	v_cvt_pk_bf16_f32 v3, v42, v43
	v_lshlrev_b32_e32 v200, 11, v10
	s_waitcnt lgkmcnt(5)
	v_cvt_pk_bf16_f32 v4, v44, v45
	s_waitcnt lgkmcnt(4)
	v_cvt_pk_bf16_f32 v5, v46, v47
	v_lshl_add_u64 v[10:11], v[8:9], 0, v[200:201]
	global_store_dwordx4 v[10:11], v[2:5], off
	s_waitcnt lgkmcnt(3)
	s_nop 0
	v_cvt_pk_bf16_f32 v2, v48, v49
	s_waitcnt lgkmcnt(2)
	v_cvt_pk_bf16_f32 v3, v50, v51
	s_waitcnt lgkmcnt(1)
	v_cvt_pk_bf16_f32 v4, v52, v53
	v_or_b32_e32 v1, 24, v233
	v_or_b32_e32 v1, s40, v1
	v_lshlrev_b32_e32 v200, 11, v1
	s_waitcnt lgkmcnt(0)
	v_cvt_pk_bf16_f32 v5, v96, v97
	v_lshl_add_u64 v[6:7], v[8:9], 0, v[200:201]
	global_store_dwordx4 v[6:7], v[2:5], off
	s_waitcnt lgkmcnt(0)

; template <bool MAP> __device__ __forceinline__ void p0_transpose_item(const float* W, int K, int NS, bf16* WT, LAS float* scr, int item, int nkb, int lane) {
;     ...
; #pragma unroll 8
;     for (int i = 0; i < 32; ++i) { const int kk = 2 * i + (lane >> 5); scr[kk * 33 + (lane & 31)] = W[(size_t)(k0 + kk) * NS + sc]; }
.LBB0_436:
	s_lshl_b32 s41, s8, 1
	s_lshl_b32 s42, s9, 1
	v_or_b32_e32 v200, s42, v6
	s_add_i32 s44, s41, 4
	s_add_i32 s45, s42, 4
	v_mov_b32_e32 v11, v201
	s_add_i32 s64, s42, 8
	v_lshlrev_b64 v[24:25], 12, v[200:201]
	v_or_b32_e32 v10, s44, v1
	v_or_b32_e32 v200, s45, v6
	v_mov_b32_e32 v9, v201
	v_or_b32_e32 v8, s41, v1
	s_add_i32 s66, s42, 12
	v_lshlrev_b64 v[10:11], 12, v[10:11]
	v_lshlrev_b64 v[26:27], 12, v[200:201]
	v_or_b32_e32 v200, s64, v6
	s_add_i32 s63, s41, 8
	s_add_i32 s65, s41, 12
	s_add_i32 s68, s42, 16
	v_lshlrev_b64 v[8:9], 12, v[8:9]
	v_lshl_add_u64 v[24:25], v[2:3], 0, v[24:25]
	v_lshl_add_u64 v[10:11], v[2:3], 0, v[10:11]
	v_lshlrev_b64 v[28:29], 12, v[200:201]
	v_or_b32_e32 v200, s66, v6
	v_mov_b32_e32 v13, v201
	v_mov_b32_e32 v15, v201
	s_add_i32 s70, s42, 20
	v_or_b32_e32 v12, s63, v1
	v_or_b32_e32 v14, s65, v1
	v_lshl_add_u64 v[8:9], v[2:3], 0, v[8:9]
	v_lshl_add_u64 v[26:27], v[2:3], 0, v[26:27]
	global_load_dword v5, v[24:25], off
	global_load_dword v7, v[8:9], off
	global_load_dword v40, v[26:27], off
	global_load_dword v41, v[10:11], off
	v_lshlrev_b64 v[10:11], 12, v[200:201]
	v_or_b32_e32 v200, s68, v6
	s_add_i32 s67, s41, 16
	s_add_i32 s69, s41, 20
	s_add_i32 s72, s42, 24
	v_lshlrev_b64 v[12:13], 12, v[12:13]
	v_lshlrev_b64 v[14:15], 12, v[14:15]
	v_lshl_add_u64 v[8:9], v[2:3], 0, v[28:29]
	v_lshl_add_u64 v[10:11], v[2:3], 0, v[10:11]
	v_lshlrev_b64 v[24:25], 12, v[200:201]
	v_or_b32_e32 v200, s70, v6
	v_mov_b32_e32 v17, v201
	v_mov_b32_e32 v19, v201
	s_add_i32 s71, s41, 24
	s_add_i32 s73, s41, 28
	s_add_i32 s74, s42, 28
	v_or_b32_e32 v16, s67, v1
	v_or_b32_e32 v18, s69, v1
	v_lshl_add_u64 v[12:13], v[2:3], 0, v[12:13]
	v_lshl_add_u64 v[14:15], v[2:3], 0, v[14:15]
	global_load_dword v42, v[8:9], off
	global_load_dword v43, v[12:13], off
	global_load_dword v44, v[10:11], off
	global_load_dword v45, v[14:15], off
	v_lshlrev_b64 v[10:11], 12, v[200:201]
	v_or_b32_e32 v200, s72, v6
	v_mov_b32_e32 v21, v201
	v_mov_b32_e32 v23, v201
	v_or_b32_e32 v20, s71, v1
	v_or_b32_e32 v22, s73, v1
	v_lshlrev_b64 v[16:17], 12, v[16:17]
	v_lshlrev_b64 v[18:19], 12, v[18:19]
	v_lshl_add_u64 v[8:9], v[2:3], 0, v[24:25]
	v_lshl_add_u64 v[10:11], v[2:3], 0, v[10:11]
	v_lshlrev_b64 v[12:13], 12, v[200:201]
	v_or_b32_e32 v200, s74, v6
	v_lshlrev_b64 v[20:21], 12, v[20:21]
	v_lshlrev_b64 v[22:23], 12, v[22:23]
	v_lshl_add_u64 v[16:17], v[2:3], 0, v[16:17]
	v_lshl_add_u64 v[18:19], v[2:3], 0, v[18:19]
	global_load_dword v46, v[8:9], off
	global_load_dword v47, v[16:17], off
	global_load_dword v48, v[10:11], off
	global_load_dword v49, v[18:19], off
	v_lshl_add_u64 v[8:9], v[2:3], 0, v[12:13]
	v_lshlrev_b64 v[10:11], 12, v[200:201]
	v_lshl_add_u64 v[20:21], v[2:3], 0, v[20:21]
	v_lshl_add_u64 v[22:23], v[2:3], 0, v[22:23]
	v_lshl_add_u64 v[10:11], v[2:3], 0, v[10:11]
	global_load_dword v50, v[8:9], off
	global_load_dword v51, v[20:21], off
	global_load_dword v52, v[10:11], off
	global_load_dword v53, v[22:23], off
	v_or_b32_e32 v10, s41, v199
	v_or_b32_e32 v8, s42, v198
	s_add_i32 s9, s9, 16
	s_add_i32 s8, s8, 16
	s_add_i32 s40, s40, -16
	v_or_b32_e32 v18, s63, v199
	v_or_b32_e32 v16, s64, v198
	v_or_b32_e32 v22, s65, v199
	v_or_b32_e32 v20, s66, v198
	v_or_b32_e32 v26, s67, v199
	v_or_b32_e32 v24, s68, v198
	v_or_b32_e32 v30, s69, v199
	v_or_b32_e32 v28, s70, v198
	v_or_b32_e32 v34, s71, v199
	v_or_b32_e32 v32, s72, v198
	v_or_b32_e32 v38, s73, v199
	v_or_b32_e32 v36, s74, v198
	s_cmp_lg_u32 s40, 0
	v_mad_u64_u32 v[8:9], s[42:43], v8, s46, v[4:5]
	v_mad_u64_u32 v[10:11], s[42:43], v10, s46, v[4:5]
	v_or_b32_e32 v9, s44, v199
	v_or_b32_e32 v11, s45, v198
	v_mad_u64_u32 v[12:13], s[42:43], v11, s46, v[4:5]
	v_mad_u64_u32 v[14:15], s[42:43], v9, s46, v[4:5]
	v_mad_u64_u32 v[16:17], s[42:43], v16, s46, v[4:5]
	v_mad_u64_u32 v[18:19], s[42:43], v18, s46, v[4:5]
	v_mad_u64_u32 v[20:21], s[42:43], v20, s46, v[4:5]
	v_mad_u64_u32 v[22:23], s[42:43], v22, s46, v[4:5]
	v_mad_u64_u32 v[24:25], s[42:43], v24, s46, v[4:5]
	v_mad_u64_u32 v[26:27], s[42:43], v26, s46, v[4:5]
	v_mad_u64_u32 v[28:29], s[42:43], v28, s46, v[4:5]
	v_mad_u64_u32 v[30:31], s[42:43], v30, s46, v[4:5]
	v_mad_u64_u32 v[32:33], s[42:43], v32, s46, v[4:5]
	v_mad_u64_u32 v[34:35], s[42:43], v34, s46, v[4:5]
	v_mad_u64_u32 v[36:37], s[42:43], v36, s46, v[4:5]
	v_mad_u64_u32 v[38:39], s[42:43], v38, s46, v[4:5]
	s_lshl_b32 s41, s8, 1
	s_lshl_b32 s42, s9, 1
	v_or_b32_e32 v200, s42, v6
	s_add_i32 s44, s41, 4
	s_add_i32 s45, s42, 4
	v_mov_b32_e32 v67, v201
	s_add_i32 s64, s42, 8
	v_lshlrev_b64 v[80:81], 12, v[200:201]
	v_or_b32_e32 v66, s44, v1
	v_or_b32_e32 v200, s45, v6
	v_mov_b32_e32 v65, v201
	v_or_b32_e32 v64, s41, v1
	s_add_i32 s66, s42, 12
	v_lshlrev_b64 v[66:67], 12, v[66:67]
	v_lshlrev_b64 v[82:83], 12, v[200:201]
	v_or_b32_e32 v200, s64, v6
	s_add_i32 s63, s41, 8
	s_add_i32 s65, s41, 12
	s_add_i32 s68, s42, 16
	v_lshlrev_b64 v[64:65], 12, v[64:65]
	v_lshl_add_u64 v[80:81], v[2:3], 0, v[80:81]
	v_lshl_add_u64 v[66:67], v[2:3], 0, v[66:67]
	v_lshlrev_b64 v[84:85], 12, v[200:201]
	v_or_b32_e32 v200, s66, v6
	v_mov_b32_e32 v69, v201
	v_mov_b32_e32 v71, v201
	s_add_i32 s70, s42, 20
	v_or_b32_e32 v68, s63, v1
	v_or_b32_e32 v70, s65, v1
	v_lshl_add_u64 v[64:65], v[2:3], 0, v[64:65]
	v_lshl_add_u64 v[82:83], v[2:3], 0, v[82:83]
	global_load_dword v61, v[80:81], off
	global_load_dword v63, v[64:65], off
	global_load_dword v96, v[82:83], off
	global_load_dword v97, v[66:67], off
	v_lshlrev_b64 v[66:67], 12, v[200:201]
	v_or_b32_e32 v200, s68, v6
	s_add_i32 s67, s41, 16
	s_add_i32 s69, s41, 20
	s_add_i32 s72, s42, 24
	v_lshlrev_b64 v[68:69], 12, v[68:69]
	v_lshlrev_b64 v[70:71], 12, v[70:71]
; template <bool MAP> __device__ __forceinline__ void p0_transpose_item(const float* W, int K, int NS, bf16* WT, LAS float* scr, int item, int nkb, int lane) {
;     ...
;     for (int i = 0; i < 32; ++i) { const int kk = 2 * i + (lane >> 5); scr[kk * 33 + (lane & 31)] = W[(size_t)(k0 + kk) * NS + sc]; }
	v_lshl_add_u64 v[64:65], v[2:3], 0, v[84:85]
	v_lshl_add_u64 v[66:67], v[2:3], 0, v[66:67]
	v_lshlrev_b64 v[80:81], 12, v[200:201]
	v_or_b32_e32 v200, s70, v6
	v_mov_b32_e32 v73, v201
	v_mov_b32_e32 v75, v201
	s_add_i32 s71, s41, 24
	s_add_i32 s73, s41, 28
	s_add_i32 s74, s42, 28
	v_or_b32_e32 v72, s67, v1
	v_or_b32_e32 v74, s69, v1
	v_lshl_add_u64 v[68:69], v[2:3], 0, v[68:69]
	v_lshl_add_u64 v[70:71], v[2:3], 0, v[70:71]
	global_load_dword v98, v[64:65], off
	global_load_dword v99, v[68:69], off
	global_load_dword v100, v[66:67], off
	global_load_dword v101, v[70:71], off
	v_lshlrev_b64 v[66:67], 12, v[200:201]
	v_or_b32_e32 v200, s72, v6
	v_mov_b32_e32 v77, v201
	v_mov_b32_e32 v79, v201
	v_or_b32_e32 v76, s71, v1
	v_or_b32_e32 v78, s73, v1
	v_lshlrev_b64 v[72:73], 12, v[72:73]
	v_lshlrev_b64 v[74:75], 12, v[74:75]
	v_lshl_add_u64 v[64:65], v[2:3], 0, v[80:81]
	v_lshl_add_u64 v[66:67], v[2:3], 0, v[66:67]
	v_lshlrev_b64 v[68:69], 12, v[200:201]
	v_or_b32_e32 v200, s74, v6
	v_lshlrev_b64 v[76:77], 12, v[76:77]
	v_lshlrev_b64 v[78:79], 12, v[78:79]
	v_lshl_add_u64 v[72:73], v[2:3], 0, v[72:73]
	v_lshl_add_u64 v[74:75], v[2:3], 0, v[74:75]
	global_load_dword v102, v[64:65], off
	global_load_dword v103, v[72:73], off
	global_load_dword v104, v[66:67], off
	global_load_dword v105, v[74:75], off
	v_lshl_add_u64 v[64:65], v[2:3], 0, v[68:69]
	v_lshlrev_b64 v[66:67], 12, v[200:201]
	v_lshl_add_u64 v[76:77], v[2:3], 0, v[76:77]
	v_lshl_add_u64 v[78:79], v[2:3], 0, v[78:79]
	v_lshl_add_u64 v[66:67], v[2:3], 0, v[66:67]
	global_load_dword v106, v[64:65], off
	global_load_dword v107, v[76:77], off
	global_load_dword v108, v[66:67], off
	global_load_dword v109, v[78:79], off
	s_waitcnt vmcnt(31)
	ds_write_b32 v8, v5
	s_waitcnt vmcnt(30)
	ds_write_b32 v10, v7
	s_waitcnt vmcnt(29)
	ds_write_b32 v12, v40
	s_waitcnt vmcnt(28)
	ds_write_b32 v14, v41
	s_waitcnt vmcnt(27)
	ds_write_b32 v16, v42
	s_waitcnt vmcnt(26)
	ds_write_b32 v18, v43
	s_waitcnt vmcnt(25)
	ds_write_b32 v20, v44
	s_waitcnt vmcnt(24)
	ds_write_b32 v22, v45
	s_waitcnt vmcnt(23)
	ds_write_b32 v24, v46
	s_waitcnt vmcnt(22)
	ds_write_b32 v26, v47
	s_waitcnt vmcnt(21)
	ds_write_b32 v28, v48
	s_waitcnt vmcnt(20)
	ds_write_b32 v30, v49
	s_waitcnt vmcnt(19)
	ds_write_b32 v32, v50
	s_waitcnt vmcnt(18)
	ds_write_b32 v34, v51
	s_waitcnt vmcnt(17)
	ds_write_b32 v36, v52
	s_waitcnt vmcnt(16)
	ds_write_b32 v38, v53
	v_or_b32_e32 v10, s41, v199
	v_or_b32_e32 v8, s42, v198
	s_add_i32 s9, s9, 16
	s_add_i32 s8, s8, 16
	s_add_i32 s40, s40, -16
	v_or_b32_e32 v18, s63, v199
	v_or_b32_e32 v16, s64, v198
	v_or_b32_e32 v22, s65, v199
	v_or_b32_e32 v20, s66, v198
	v_or_b32_e32 v26, s67, v199
	v_or_b32_e32 v24, s68, v198
	v_or_b32_e32 v30, s69, v199
	v_or_b32_e32 v28, s70, v198
	v_or_b32_e32 v34, s71, v199
	v_or_b32_e32 v32, s72, v198
	v_or_b32_e32 v38, s73, v199
	v_or_b32_e32 v36, s74, v198
	s_cmp_lg_u32 s40, 0
	v_mad_u64_u32 v[8:9], s[42:43], v8, s46, v[4:5]
	v_mad_u64_u32 v[10:11], s[42:43], v10, s46, v[4:5]
	v_or_b32_e32 v9, s44, v199
	v_or_b32_e32 v11, s45, v198
	v_mad_u64_u32 v[12:13], s[42:43], v11, s46, v[4:5]
	v_mad_u64_u32 v[14:15], s[42:43], v9, s46, v[4:5]
	v_mad_u64_u32 v[16:17], s[42:43], v16, s46, v[4:5]
	v_mad_u64_u32 v[18:19], s[42:43], v18, s46, v[4:5]
	v_mad_u64_u32 v[20:21], s[42:43], v20, s46, v[4:5]
	v_mad_u64_u32 v[22:23], s[42:43], v22, s46, v[4:5]
	v_mad_u64_u32 v[24:25], s[42:43], v24, s46, v[4:5]
	v_mad_u64_u32 v[26:27], s[42:43], v26, s46, v[4:5]
	v_mad_u64_u32 v[28:29], s[42:43], v28, s46, v[4:5]
	v_mad_u64_u32 v[30:31], s[42:43], v30, s46, v[4:5]
	v_mad_u64_u32 v[32:33], s[42:43], v32, s46, v[4:5]
	v_mad_u64_u32 v[34:35], s[42:43], v34, s46, v[4:5]
	v_mad_u64_u32 v[36:37], s[42:43], v36, s46, v[4:5]
	v_mad_u64_u32 v[38:39], s[42:43], v38, s46, v[4:5]
	s_waitcnt vmcnt(15)
; #define GAS __attribute__((address_space(1)))
; #define LAS __attribute__((address_space(3)))
; #define LDS_WAIT() asm volatile("s_waitcnt lgkmcnt(0)" ::: "memory")
; __device__ __forceinline__ unsigned pk2(float lo, float hi) { return pg8::cvt_pk_bf16(lo, hi); }
; template <bool MAP> __device__ __forceinline__ void p0_transpose_item(const float* W, int K, int NS, bf16* WT, LAS float* scr, int item, int nkb, int lane) {
;     ...
;     for (int i = 0; i < 32; ++i) { const int kk = 2 * i + (lane >> 5); scr[kk * 33 + (lane & 31)] = W[(size_t)(k0 + kk) * NS + sc]; }
;     LDS_WAIT(); asm volatile("" ::: "memory");
;     const int c = lane & 7;
; #pragma unroll
;     for (int j = 0; j < 4; ++j) { const int n = (lane >> 3) + 8 * j; const LAS float* s = scr + (8 * c) * 33 + n;
;         v4u o; o.x = pk2(s[0 * 33], s[1 * 33]); o.y = pk2(s[2 * 33], s[3 * 33]); o.z = pk2(s[4 * 33], s[5 * 33]); o.w = pk2(s[6 * 33], s[7 * 33]);
;         *(GAS v4u*)(WT + (size_t)(p0 + n) * K + k0 + 8 * c) = o; }
;     LDS_WAIT(); asm volatile("" ::: "memory");
	ds_write_b32 v8, v61
	s_waitcnt vmcnt(14)
	ds_write_b32 v10, v63
	s_waitcnt vmcnt(13)
	ds_write_b32 v12, v96
	s_waitcnt vmcnt(12)
	ds_write_b32 v14, v97
	s_waitcnt vmcnt(11)
	ds_write_b32 v16, v98
	s_waitcnt vmcnt(10)
	ds_write_b32 v18, v99
	s_waitcnt vmcnt(9)
	ds_write_b32 v20, v100
	s_waitcnt vmcnt(8)
	ds_write_b32 v22, v101
	s_waitcnt vmcnt(7)
	ds_write_b32 v24, v102
	s_waitcnt vmcnt(6)
	ds_write_b32 v26, v103
	s_waitcnt vmcnt(5)
	ds_write_b32 v28, v104
	s_waitcnt vmcnt(4)
	ds_write_b32 v30, v105
	s_waitcnt vmcnt(3)
	ds_write_b32 v32, v106
	s_waitcnt vmcnt(2)
	ds_write_b32 v34, v107
	s_waitcnt vmcnt(1)
	ds_write_b32 v36, v108
	s_waitcnt vmcnt(0)
	ds_write_b32 v38, v109
	s_lshl_b32 s8, s11, 1
	s_waitcnt lgkmcnt(0)
	v_lshlrev_b32_e32 v1, 2, v233
	v_mul_u32_u24_e32 v2, 0x84, v204
	s_add_u32 s6, s6, s8
	v_add3_u32 v1, s12, v2, v1
	v_lshlrev_b32_e32 v200, 1, v204
	s_addc_u32 s7, s7, 0
	ds_read2_b32 v[40:41], v1 offset1:33
	ds_read2_b32 v[42:43], v1 offset0:66 offset1:99
	ds_read2_b32 v[44:45], v1 offset0:132 offset1:165
	ds_read2_b32 v[46:47], v1 offset0:198 offset1:231
	ds_read2_b32 v[48:49], v1 offset0:8 offset1:41
	ds_read2_b32 v[50:51], v1 offset0:74 offset1:107
	ds_read2_b32 v[52:53], v1 offset0:140 offset1:173
	ds_read2_b32 v[96:97], v1 offset0:206 offset1:239
	v_or_b32_e32 v10, s10, v233
	v_lshl_add_u64 v[8:9], s[6:7], 0, v[200:201]
	s_waitcnt lgkmcnt(7)
	v_cvt_pk_bf16_f32 v2, v40, v41
	ds_read2_b32 v[40:41], v1 offset0:16 offset1:49
	v_lshlrev_b32_e32 v200, 11, v10
	v_lshl_add_u64 v[8:9], v[8:9], 0, s[38:39]
	s_waitcnt lgkmcnt(7)
	v_cvt_pk_bf16_f32 v3, v42, v43
	ds_read2_b32 v[42:43], v1 offset0:82 offset1:115
	v_lshl_add_u64 v[10:11], v[8:9], 0, v[200:201]
	s_waitcnt lgkmcnt(7)
	v_cvt_pk_bf16_f32 v4, v44, v45
	ds_read2_b32 v[44:45], v1 offset0:148 offset1:181
	s_waitcnt lgkmcnt(7)
	v_cvt_pk_bf16_f32 v5, v46, v47
	ds_read2_b32 v[46:47], v1 offset0:214 offset1:247
	global_store_dwordx4 v[10:11], v[2:5], off
	v_or_b32_e32 v10, 8, v233
	v_or_b32_e32 v10, s10, v10
	s_waitcnt lgkmcnt(7)
	v_cvt_pk_bf16_f32 v2, v48, v49
	ds_read2_b32 v[48:49], v1 offset0:24 offset1:57
	v_lshlrev_b32_e32 v200, 11, v10
	s_waitcnt lgkmcnt(7)
	v_cvt_pk_bf16_f32 v3, v50, v51
	ds_read2_b32 v[50:51], v1 offset0:90 offset1:123
	v_lshl_add_u64 v[10:11], v[8:9], 0, v[200:201]
	s_waitcnt lgkmcnt(7)
	v_cvt_pk_bf16_f32 v4, v52, v53
	ds_read2_b32 v[52:53], v1 offset0:156 offset1:189
	s_waitcnt lgkmcnt(7)
	v_cvt_pk_bf16_f32 v5, v96, v97
	ds_read2_b32 v[96:97], v1 offset0:222 offset1:255
	global_store_dwordx4 v[10:11], v[2:5], off
	v_or_b32_e32 v10, 16, v233
	s_waitcnt lgkmcnt(7)
	v_cvt_pk_bf16_f32 v2, v40, v41
	v_or_b32_e32 v10, s10, v10
	s_waitcnt lgkmcnt(6)
	v_cvt_pk_bf16_f32 v3, v42, v43
	v_lshlrev_b32_e32 v200, 11, v10
	s_waitcnt lgkmcnt(5)
	v_cvt_pk_bf16_f32 v4, v44, v45
	s_waitcnt lgkmcnt(4)
	v_cvt_pk_bf16_f32 v5, v46, v47
	v_lshl_add_u64 v[10:11], v[8:9], 0, v[200:201]
	global_store_dwordx4 v[10:11], v[2:5], off
	s_waitcnt lgkmcnt(3)
	s_nop 0
	v_cvt_pk_bf16_f32 v2, v48, v49
	s_waitcnt lgkmcnt(2)
	v_cvt_pk_bf16_f32 v3, v50, v51
	s_waitcnt lgkmcnt(1)
	v_cvt_pk_bf16_f32 v4, v52, v53
	v_or_b32_e32 v1, 24, v233
	v_or_b32_e32 v1, s10, v1
	v_lshlrev_b32_e32 v200, 11, v1
	s_waitcnt lgkmcnt(0)
	v_cvt_pk_bf16_f32 v5, v96, v97
	v_lshl_add_u64 v[6:7], v[8:9], 0, v[200:201]
	global_store_dwordx4 v[6:7], v[2:5], off
	s_waitcnt lgkmcnt(0)
	s_branch .LBB0_340
